# v66 plus 8 more bit-trick bf16 RNE packs replaced by v_cvt_pk_bf16_f32 (early placement)
# speedup vs baseline: 1.0013x; 1.0013x over previous
; #define LAS __attribute__((address_space(3)))
; template <int L>
; __device__ __forceinline__ void layer_body(const Args& args, LAS unsigned char* lds, const int wave, const int G, const int gw, const int NGW, const int lo, const int hi,
;                                            unsigned char* const ws_kernel, const XcdBarrier& bar, int& pid) {
;     ...
;                     sum += __shfl_xor(sum, 16); sum += __shfl_xor(sum, 32);
;                     bf16x8 pbf[8];
; #pragma unroll
;                     for (int s = 0; s < 8; ++s) { const f32x4 p0 = sc[2 * s], p1 = sc[2 * s + 1]; v4u w; w.x = pk2(p0[0], p0[1]); w.y = pk2(p0[2], p0[3]); w.z = pk2(p1[0], p1[1]); w.w = pk2(p1[2], p1[3]); pbf[s] = __builtin_bit_cast(bf16x8, w); }
;                     __syncthreads();
; #pragma unroll
;                     for (int i = 0; i < 14; ++i) { const int kid = skey + 32 * i; *(LAS v4u*)(size_t)(IMG + vimg_off(kid, sch)) = rst[i]; }
;                     __syncthreads();
;                     if (unit + GH < UEND) { NA_LOADROWS(unit + GH, rst, D); NA_LOADQ(unit + GH); }
;                     f32x4 acc[8];
; #pragma unroll
;                     for (int mt = 0; mt < 8; ++mt) acc[mt] = (f32x4){0.f, 0.f, 0.f, 0.f};
;                     const int trq = (lane & 15) >> 2, trp = lane & 3;
; #pragma unroll
;                     for (int s = 0; s < 8; ++s) {
;                         const int ir0 = (r0w - krlo + s) * 40 + coloff;
; #pragma unroll
;                         for (int mh = 0; mh < 2; ++mh) {
;                             s16x4 lo[4], hi[4];
; #pragma unroll
;                             for (int m4 = 0; m4 < 4; ++m4) { const int mt = mh * 4 + m4, r0_ = ir0 + 4 * kg + trq, r1_ = ir0 + 16 + 4 * kg + trq, ch_ = 2 * mt + (trp >> 1);
;                                 lo[m4] = tr_read_b64(IMG + vimg_off(r0_, ch_) + 8u * (trp & 1)); hi[m4] = tr_read_b64(IMG + vimg_off(r1_, ch_) + 8u * (trp & 1)); }
;                             asm volatile("s_waitcnt lgkmcnt(0)" ::: "memory"); __builtin_amdgcn_sched_barrier(0);
; #pragma unroll
;                             for (int m4 = 0; m4 < 4; ++m4) { const int mt = mh * 4 + m4; const bf16x8 va = (bf16x8){lo[m4][0], lo[m4][1], lo[m4][2], lo[m4][3], hi[m4][0], hi[m4][1], hi[m4][2], hi[m4][3]};
;                                 acc[mt] = __builtin_amdgcn_mfma_f32_16x16x32_bf16(va, pbf[s], acc[mt], 0, 0, 0); }
.LBB0_843:
	v_cvt_pk_bf16_f32 v101, v196, v202
	v_cvt_pk_bf16_f32 v100, v192, v200
	v_cvt_pk_bf16_f32 v103, v201, v204
	v_cvt_pk_bf16_f32 v102, v198, v203
	v_cvt_pk_bf16_f32 v97, v186, v195
	v_cvt_pk_bf16_f32 v96, v182, v193
	v_cvt_pk_bf16_f32 v99, v194, v199
	v_cvt_pk_bf16_f32 v98, v189, v197
	v_cvt_pk_bf16_f32 v93, v180, v185
	v_cvt_pk_bf16_f32 v92, v179, v183
	v_cvt_pk_bf16_f32 v95, v184, v190
	v_cvt_pk_bf16_f32 v94, v181, v187
	v_cvt_pk_bf16_f32 v89, v142, v148
	v_cvt_pk_bf16_f32 v88, v138, v146
	v_cvt_pk_bf16_f32 v91, v147, v152
	v_cvt_pk_bf16_f32 v90, v144, v150
	v_cvt_pk_bf16_f32 v85, v134, v141
	v_cvt_pk_bf16_f32 v84, v130, v139
	v_cvt_pk_bf16_f32 v87, v140, v145
	v_cvt_pk_bf16_f32 v86, v136, v143
	v_cvt_pk_bf16_f32 v81, v126, v133
	v_cvt_pk_bf16_f32 v80, v122, v131
	v_cvt_pk_bf16_f32 v83, v132, v137
	v_cvt_pk_bf16_f32 v82, v128, v135
	v_cvt_pk_bf16_f32 v79, v124, v129
	v_cvt_pk_bf16_f32 v76, v75, v123
	v_cvt_pk_bf16_f32 v78, v120, v127
	v_cvt_pk_bf16_f32 v77, v118, v125
	v_bfe_u32 v114, v115, 16, 1
	v_add3_u32 v114, v115, v114, s23
	v_bfe_u32 v115, v72, 16, 1
	v_add3_u32 v72, v72, v115, s23
	v_lshrrev_b32_e32 v112, 2, v112
	v_lshrrev_b32_e32 v72, 16, v72
	v_cvt_pk_bf16_f32 v75, v116, v121
	v_or_b32_e32 v115, v110, v112
	s_add_i32 s6, s6, s15
	v_cvt_pk_bf16_f32 v73, v73, v117
	v_and_or_b32 v72, v114, s89, v72
	v_or_b32_e32 v113, 16, v115
	v_bfe_u32 v112, v111, 1, 1
	v_lshlrev_b32_e32 v111, 3, v111
	v_add_u32_e32 v114, s6, v115
	v_and_or_b32 v111, v111, 8, 0
	v_add_u32_e32 v116, s6, v113
	v_lshlrev_b32_e32 v117, 2, v114
	v_and_b32_e32 v152, 12, v117
	v_bfe_u32 v153, v114, 2, 2
	v_lshl_add_u32 v154, v114, 8, v111
	v_lshlrev_b32_e32 v114, 2, v116
	v_and_b32_e32 v155, 12, v114
	v_bitop3_b32 v114, v152, v112, v153 bitop3:0x36
	v_bfe_u32 v156, v116, 2, 2
	v_lshl_add_u32 v253, v114, 4, v154
	v_lshl_add_u32 v157, v116, 8, v111
	ds_read_b64_tr_b16 v[120:121], v253
	v_bitop3_b32 v114, v155, v112, v156 bitop3:0x36
	v_lshl_add_u32 v252, v114, 4, v157
	ds_read_b64_tr_b16 v[122:123], v252
	v_xor_b32_e32 v116, 0x20, v253
	ds_read_b64_tr_b16 v[124:125], v116
	v_xor_b32_e32 v116, 0x20, v252
	ds_read_b64_tr_b16 v[126:127], v116
	v_or_b32_e32 v116, 4, v112
	v_xor_b32_e32 v117, 0x40, v253
	ds_read_b64_tr_b16 v[128:129], v117
	v_xor_b32_e32 v117, 0x40, v252
	ds_read_b64_tr_b16 v[130:131], v117
	v_xor_b32_e32 v118, 0x60, v253
	ds_read_b64_tr_b16 v[132:133], v118
	v_xor_b32_e32 v118, 0x60, v252
	ds_read_b64_tr_b16 v[134:135], v118
	s_waitcnt lgkmcnt(0)
	v_cvt_pk_bf16_f32 v74, v74, v119
	v_add_f32_e32 v104, v149, v151
	v_xor_b32_e32 v119, 0x80, v253
	v_mfma_f32_16x16x32_bf16 v[136:139], v[120:123], v[100:103], 0
	ds_read_b64_tr_b16 v[122:123], v119
	v_xor_b32_e32 v119, 0x80, v252
	v_mfma_f32_16x16x32_bf16 v[140:143], v[124:127], v[100:103], 0
	ds_read_b64_tr_b16 v[124:125], v119
	v_xor_b32_e32 v120, 0xa0, v253
	v_mfma_f32_16x16x32_bf16 v[126:129], v[128:131], v[100:103], 0
	ds_read_b64_tr_b16 v[130:131], v120
	v_xor_b32_e32 v120, 0xa0, v252
	v_mfma_f32_16x16x32_bf16 v[144:147], v[132:135], v[100:103], 0
	ds_read_b64_tr_b16 v[132:133], v120
	v_xor_b32_e32 v121, 0xc0, v253
	ds_read_b64_tr_b16 v[148:149], v121
	v_xor_b32_e32 v121, 0xc0, v252
	ds_read_b64_tr_b16 v[150:151], v121
	v_or_b32_e32 v121, 14, v112
	v_xor_b32_e32 v134, 0xe0, v253
	ds_read_b64_tr_b16 v[152:153], v134
	v_xor_b32_e32 v134, 0xe0, v252
	ds_read_b64_tr_b16 v[154:155], v134
	s_waitcnt lgkmcnt(0)
	s_add_i32 s7, s7, s15
	v_add_u32_e32 v134, s7, v115
	v_add_u32_e32 v135, s7, v113
	v_lshlrev_b32_e32 v156, 2, v134
	v_and_b32_e32 v168, 12, v156
	v_bfe_u32 v169, v134, 2, 2
	v_lshl_add_u32 v170, v134, 8, v111
	v_lshlrev_b32_e32 v134, 2, v135
	v_and_b32_e32 v171, 12, v134
	v_bitop3_b32 v134, v168, v112, v169 bitop3:0x36
	v_bfe_u32 v172, v135, 2, 2
	v_lshl_add_u32 v253, v134, 4, v170
	v_mfma_f32_16x16x32_bf16 v[122:125], v[122:125], v[100:103], 0
	v_lshl_add_u32 v173, v135, 8, v111
	v_mfma_f32_16x16x32_bf16 v[130:133], v[130:133], v[100:103], 0
	v_mfma_f32_16x16x32_bf16 v[148:151], v[148:151], v[100:103], 0
	v_mfma_f32_16x16x32_bf16 v[100:103], v[152:155], v[100:103], 0
	ds_read_b64_tr_b16 v[152:153], v253
	v_bitop3_b32 v134, v171, v112, v172 bitop3:0x36
	v_lshl_add_u32 v252, v134, 4, v173
	ds_read_b64_tr_b16 v[154:155], v252
	v_xor_b32_e32 v134, 0x20, v253
	ds_read_b64_tr_b16 v[156:157], v134
	v_xor_b32_e32 v134, 0x20, v252
	ds_read_b64_tr_b16 v[158:159], v134
	v_xor_b32_e32 v134, 0x40, v253
	ds_read_b64_tr_b16 v[160:161], v134
	v_xor_b32_e32 v134, 0x40, v252
	ds_read_b64_tr_b16 v[162:163], v134
	v_xor_b32_e32 v134, 0x60, v253
	ds_read_b64_tr_b16 v[164:165], v134
	v_xor_b32_e32 v134, 0x60, v252
	ds_read_b64_tr_b16 v[166:167], v134
	s_waitcnt lgkmcnt(0)
	v_mfma_f32_16x16x32_bf16 v[134:137], v[152:155], v[96:99], v[136:139]
	v_mfma_f32_16x16x32_bf16 v[138:141], v[156:159], v[96:99], v[140:143]
	v_mfma_f32_16x16x32_bf16 v[142:145], v[164:167], v[96:99], v[144:147]
	s_nop 2
	v_xor_b32_e32 v146, 0x80, v253
	ds_read_b64_tr_b16 v[152:153], v146
	v_xor_b32_e32 v146, 0x80, v252
	ds_read_b64_tr_b16 v[154:155], v146
	v_xor_b32_e32 v146, 0xa0, v253
	ds_read_b64_tr_b16 v[156:157], v146
	v_xor_b32_e32 v146, 0xa0, v252
	ds_read_b64_tr_b16 v[158:159], v146
	v_xor_b32_e32 v146, 0xc0, v253
	v_mfma_f32_16x16x32_bf16 v[126:129], v[160:163], v[96:99], v[126:129]
	ds_read_b64_tr_b16 v[160:161], v146
	v_xor_b32_e32 v146, 0xc0, v252
	ds_read_b64_tr_b16 v[162:163], v146
	v_xor_b32_e32 v146, 0xe0, v253
	ds_read_b64_tr_b16 v[164:165], v146
	v_xor_b32_e32 v146, 0xe0, v252
	ds_read_b64_tr_b16 v[166:167], v146
	s_waitcnt lgkmcnt(0)
; __device__ __forceinline__ s16x4 tr_read_b64(unsigned addr) { s16x4 r; asm volatile("ds_read_b64_tr_b16 %0, %1" : "=v"(r) : "v"(addr) : "memory"); return r; }
; template <int L>
; __device__ __forceinline__ void layer_body(const Args& args, LAS unsigned char* lds, const int wave, const int G, const int gw, const int NGW, const int lo, const int hi,
;                                            unsigned char* const ws_kernel, const XcdBarrier& bar, int& pid) {
;     ...
;                     for (int s = 0; s < 8; ++s) {
;                         const int ir0 = (r0w - krlo + s) * 40 + coloff;
; #pragma unroll
;                         for (int mh = 0; mh < 2; ++mh) {
;                             s16x4 lo[4], hi[4];
; #pragma unroll
;                             for (int m4 = 0; m4 < 4; ++m4) { const int mt = mh * 4 + m4, r0_ = ir0 + 4 * kg + trq, r1_ = ir0 + 16 + 4 * kg + trq, ch_ = 2 * mt + (trp >> 1);
;                                 lo[m4] = tr_read_b64(IMG + vimg_off(r0_, ch_) + 8u * (trp & 1)); hi[m4] = tr_read_b64(IMG + vimg_off(r1_, ch_) + 8u * (trp & 1)); }
;                             asm volatile("s_waitcnt lgkmcnt(0)" ::: "memory"); __builtin_amdgcn_sched_barrier(0);
; #pragma unroll
;                             for (int m4 = 0; m4 < 4; ++m4) { const int mt = mh * 4 + m4; const bf16x8 va = (bf16x8){lo[m4][0], lo[m4][1], lo[m4][2], lo[m4][3], hi[m4][0], hi[m4][1], hi[m4][2], hi[m4][3]};
;                                 acc[mt] = __builtin_amdgcn_mfma_f32_16x16x32_bf16(va, pbf[s], acc[mt], 0, 0, 0); }
	s_add_i32 s8, s8, s15
	v_mfma_f32_16x16x32_bf16 v[122:125], v[152:155], v[96:99], v[122:125]
	v_mfma_f32_16x16x32_bf16 v[130:133], v[156:159], v[96:99], v[130:133]
	v_mfma_f32_16x16x32_bf16 v[146:149], v[160:163], v[96:99], v[148:151]
	v_mfma_f32_16x16x32_bf16 v[96:99], v[164:167], v[96:99], v[100:103]
	s_nop 2
	v_add_u32_e32 v100, s8, v115
	v_add_u32_e32 v101, s8, v113
	v_lshlrev_b32_e32 v102, 2, v100
	v_and_b32_e32 v162, 12, v102
	v_bfe_u32 v163, v100, 2, 2
	v_lshl_add_u32 v164, v100, 8, v111
	v_lshlrev_b32_e32 v100, 2, v101
	v_and_b32_e32 v165, 12, v100
	v_bfe_u32 v166, v101, 2, 2
	v_bitop3_b32 v100, v162, v112, v163 bitop3:0x36
	v_lshl_add_u32 v167, v101, 8, v111
	v_lshl_add_u32 v253, v100, 4, v164
	v_bitop3_b32 v102, v165, v112, v166 bitop3:0x36
	ds_read_b64_tr_b16 v[100:101], v253
	v_lshl_add_u32 v252, v102, 4, v167
	ds_read_b64_tr_b16 v[102:103], v252
	v_xor_b32_e32 v150, 0x20, v253
	ds_read_b64_tr_b16 v[150:151], v150
	v_xor_b32_e32 v152, 0x20, v252
	ds_read_b64_tr_b16 v[152:153], v152
	v_xor_b32_e32 v154, 0x40, v253
	ds_read_b64_tr_b16 v[154:155], v154
	v_xor_b32_e32 v156, 0x40, v252
	ds_read_b64_tr_b16 v[156:157], v156
	v_xor_b32_e32 v158, 0x60, v253
	ds_read_b64_tr_b16 v[158:159], v158
	v_xor_b32_e32 v160, 0x60, v252
	ds_read_b64_tr_b16 v[160:161], v160
	s_waitcnt lgkmcnt(0)
	v_mfma_f32_16x16x32_bf16 v[100:103], v[100:103], v[92:95], v[134:137]
	v_mfma_f32_16x16x32_bf16 v[134:137], v[150:153], v[92:95], v[138:141]
	v_xor_b32_e32 v150, 0xa0, v253
	v_mfma_f32_16x16x32_bf16 v[138:141], v[158:161], v[92:95], v[142:145]
	v_xor_b32_e32 v152, 0xa0, v252
	v_xor_b32_e32 v158, 0xe0, v253
	v_xor_b32_e32 v142, 0x80, v253
	ds_read_b64_tr_b16 v[142:143], v142
	v_xor_b32_e32 v144, 0x80, v252
	ds_read_b64_tr_b16 v[144:145], v144
	v_mfma_f32_16x16x32_bf16 v[126:129], v[154:157], v[92:95], v[126:129]
	ds_read_b64_tr_b16 v[150:151], v150
	ds_read_b64_tr_b16 v[152:153], v152
	v_xor_b32_e32 v154, 0xc0, v253
	ds_read_b64_tr_b16 v[154:155], v154
	v_xor_b32_e32 v156, 0xc0, v252
	ds_read_b64_tr_b16 v[156:157], v156
	ds_read_b64_tr_b16 v[158:159], v158
	v_xor_b32_e32 v160, 0xe0, v252
	ds_read_b64_tr_b16 v[160:161], v160
	s_waitcnt lgkmcnt(0)
	s_add_i32 s37, s37, s15
	v_mfma_f32_16x16x32_bf16 v[122:125], v[142:145], v[92:95], v[122:125]
	v_mfma_f32_16x16x32_bf16 v[130:133], v[150:153], v[92:95], v[130:133]
	v_mfma_f32_16x16x32_bf16 v[142:145], v[154:157], v[92:95], v[146:149]
	v_mfma_f32_16x16x32_bf16 v[92:95], v[158:161], v[92:95], v[96:99]
	s_nop 2
	v_add_u32_e32 v96, s37, v115
	v_add_u32_e32 v97, s37, v113
	v_lshlrev_b32_e32 v98, 2, v96
	v_and_b32_e32 v158, 12, v98
	v_bfe_u32 v159, v96, 2, 2
	v_lshl_add_u32 v160, v96, 8, v111
	v_lshlrev_b32_e32 v96, 2, v97
	v_and_b32_e32 v161, 12, v96
	v_bfe_u32 v162, v97, 2, 2
	v_bitop3_b32 v96, v158, v112, v159 bitop3:0x36
	v_lshl_add_u32 v163, v97, 8, v111
	v_lshl_add_u32 v253, v96, 4, v160
	v_bitop3_b32 v98, v161, v112, v162 bitop3:0x36
	ds_read_b64_tr_b16 v[96:97], v253
	v_lshl_add_u32 v252, v98, 4, v163
	ds_read_b64_tr_b16 v[98:99], v252
	v_xor_b32_e32 v146, 0x20, v253
	ds_read_b64_tr_b16 v[146:147], v146
	v_xor_b32_e32 v148, 0x20, v252
	ds_read_b64_tr_b16 v[148:149], v148
	v_xor_b32_e32 v150, 0x40, v253
	ds_read_b64_tr_b16 v[150:151], v150
	v_xor_b32_e32 v152, 0x40, v252
	ds_read_b64_tr_b16 v[152:153], v152
	v_xor_b32_e32 v154, 0x60, v253
	ds_read_b64_tr_b16 v[154:155], v154
	v_xor_b32_e32 v156, 0x60, v252
	ds_read_b64_tr_b16 v[156:157], v156
	s_waitcnt lgkmcnt(0)
	v_mfma_f32_16x16x32_bf16 v[96:99], v[96:99], v[88:91], v[100:103]
	v_mfma_f32_16x16x32_bf16 v[100:103], v[146:149], v[88:91], v[134:137]
	v_xor_b32_e32 v146, 0xa0, v253
	v_mfma_f32_16x16x32_bf16 v[134:137], v[154:157], v[88:91], v[138:141]
	v_xor_b32_e32 v148, 0xa0, v252
	v_xor_b32_e32 v154, 0xe0, v253
	v_xor_b32_e32 v138, 0x80, v253
	ds_read_b64_tr_b16 v[138:139], v138
	v_xor_b32_e32 v140, 0x80, v252
	ds_read_b64_tr_b16 v[140:141], v140
	v_mfma_f32_16x16x32_bf16 v[126:129], v[150:153], v[88:91], v[126:129]
	ds_read_b64_tr_b16 v[146:147], v146
	ds_read_b64_tr_b16 v[148:149], v148
	v_xor_b32_e32 v150, 0xc0, v253
	ds_read_b64_tr_b16 v[150:151], v150
	v_xor_b32_e32 v152, 0xc0, v252
	ds_read_b64_tr_b16 v[152:153], v152
	ds_read_b64_tr_b16 v[154:155], v154
	v_xor_b32_e32 v156, 0xe0, v252
	ds_read_b64_tr_b16 v[156:157], v156
	s_waitcnt lgkmcnt(0)
	s_add_i32 s38, s38, s15
	v_mfma_f32_16x16x32_bf16 v[122:125], v[138:141], v[88:91], v[122:125]
	v_mfma_f32_16x16x32_bf16 v[130:133], v[146:149], v[88:91], v[130:133]
	v_mfma_f32_16x16x32_bf16 v[138:141], v[150:153], v[88:91], v[142:145]
	v_mfma_f32_16x16x32_bf16 v[88:91], v[154:157], v[88:91], v[92:95]
	s_nop 2
	v_add_u32_e32 v92, s38, v115
	v_add_u32_e32 v93, s38, v113
	v_lshlrev_b32_e32 v94, 2, v92
	v_and_b32_e32 v154, 12, v94
	v_bfe_u32 v155, v92, 2, 2
	v_lshl_add_u32 v156, v92, 8, v111
	v_lshlrev_b32_e32 v92, 2, v93
	v_and_b32_e32 v157, 12, v92
	v_bfe_u32 v158, v93, 2, 2
	v_bitop3_b32 v92, v154, v112, v155 bitop3:0x36
	v_lshl_add_u32 v159, v93, 8, v111
	v_lshl_add_u32 v253, v92, 4, v156
	v_bitop3_b32 v94, v157, v112, v158 bitop3:0x36
	ds_read_b64_tr_b16 v[92:93], v253
	v_lshl_add_u32 v252, v94, 4, v159
	ds_read_b64_tr_b16 v[94:95], v252
	v_xor_b32_e32 v142, 0x20, v253
	ds_read_b64_tr_b16 v[142:143], v142
	v_xor_b32_e32 v144, 0x20, v252
	ds_read_b64_tr_b16 v[144:145], v144
	v_xor_b32_e32 v146, 0x40, v253
	ds_read_b64_tr_b16 v[146:147], v146
	v_xor_b32_e32 v148, 0x40, v252
	ds_read_b64_tr_b16 v[148:149], v148
	v_xor_b32_e32 v150, 0x60, v253
	ds_read_b64_tr_b16 v[150:151], v150
	v_xor_b32_e32 v152, 0x60, v252
	ds_read_b64_tr_b16 v[152:153], v152
	s_waitcnt lgkmcnt(0)
; __device__ __forceinline__ s16x4 tr_read_b64(unsigned addr) { s16x4 r; asm volatile("ds_read_b64_tr_b16 %0, %1" : "=v"(r) : "v"(addr) : "memory"); return r; }
; template <int L>
; __device__ __forceinline__ void layer_body(const Args& args, LAS unsigned char* lds, const int wave, const int G, const int gw, const int NGW, const int lo, const int hi,
;                                            unsigned char* const ws_kernel, const XcdBarrier& bar, int& pid) {
;     ...
;                     for (int s = 0; s < 8; ++s) {
;                         const int ir0 = (r0w - krlo + s) * 40 + coloff;
; #pragma unroll
;                         for (int mh = 0; mh < 2; ++mh) {
;                             s16x4 lo[4], hi[4];
; #pragma unroll
;                             for (int m4 = 0; m4 < 4; ++m4) { const int mt = mh * 4 + m4, r0_ = ir0 + 4 * kg + trq, r1_ = ir0 + 16 + 4 * kg + trq, ch_ = 2 * mt + (trp >> 1);
;                                 lo[m4] = tr_read_b64(IMG + vimg_off(r0_, ch_) + 8u * (trp & 1)); hi[m4] = tr_read_b64(IMG + vimg_off(r1_, ch_) + 8u * (trp & 1)); }
;                             asm volatile("s_waitcnt lgkmcnt(0)" ::: "memory"); __builtin_amdgcn_sched_barrier(0);
; #pragma unroll
;                             for (int m4 = 0; m4 < 4; ++m4) { const int mt = mh * 4 + m4; const bf16x8 va = (bf16x8){lo[m4][0], lo[m4][1], lo[m4][2], lo[m4][3], hi[m4][0], hi[m4][1], hi[m4][2], hi[m4][3]};
;                                 acc[mt] = __builtin_amdgcn_mfma_f32_16x16x32_bf16(va, pbf[s], acc[mt], 0, 0, 0); }
	v_mfma_f32_16x16x32_bf16 v[92:95], v[92:95], v[84:87], v[96:99]
	v_mfma_f32_16x16x32_bf16 v[96:99], v[142:145], v[84:87], v[100:103]
	v_xor_b32_e32 v142, 0xa0, v253
	v_mfma_f32_16x16x32_bf16 v[100:103], v[146:149], v[84:87], v[126:129]
	v_xor_b32_e32 v144, 0xa0, v252
	v_xor_b32_e32 v146, 0xc0, v253
	v_mfma_f32_16x16x32_bf16 v[126:129], v[150:153], v[84:87], v[134:137]
	v_xor_b32_e32 v148, 0xc0, v252
	v_xor_b32_e32 v134, 0x80, v253
	ds_read_b64_tr_b16 v[134:135], v134
	v_xor_b32_e32 v136, 0x80, v252
	ds_read_b64_tr_b16 v[136:137], v136
	ds_read_b64_tr_b16 v[142:143], v142
	ds_read_b64_tr_b16 v[144:145], v144
	ds_read_b64_tr_b16 v[146:147], v146
	ds_read_b64_tr_b16 v[148:149], v148
	v_xor_b32_e32 v150, 0xe0, v253
	ds_read_b64_tr_b16 v[150:151], v150
	v_xor_b32_e32 v152, 0xe0, v252
	ds_read_b64_tr_b16 v[152:153], v152
	s_waitcnt lgkmcnt(0)
	s_add_i32 s39, s39, s15
	v_mfma_f32_16x16x32_bf16 v[122:125], v[134:137], v[84:87], v[122:125]
	v_mfma_f32_16x16x32_bf16 v[130:133], v[142:145], v[84:87], v[130:133]
	v_mfma_f32_16x16x32_bf16 v[134:137], v[146:149], v[84:87], v[138:141]
	v_mfma_f32_16x16x32_bf16 v[84:87], v[150:153], v[84:87], v[88:91]
	s_nop 2
	v_add_u32_e32 v88, s39, v115
	v_add_u32_e32 v89, s39, v113
	v_lshlrev_b32_e32 v90, 2, v88
	v_and_b32_e32 v150, 12, v90
	v_bfe_u32 v151, v88, 2, 2
	v_lshl_add_u32 v152, v88, 8, v111
	v_lshlrev_b32_e32 v88, 2, v89
	v_and_b32_e32 v153, 12, v88
	v_bfe_u32 v154, v89, 2, 2
	v_bitop3_b32 v88, v150, v112, v151 bitop3:0x36
	v_lshl_add_u32 v155, v89, 8, v111
	v_lshl_add_u32 v253, v88, 4, v152
	v_bitop3_b32 v90, v153, v112, v154 bitop3:0x36
	ds_read_b64_tr_b16 v[88:89], v253
	v_lshl_add_u32 v252, v90, 4, v155
	ds_read_b64_tr_b16 v[90:91], v252
	v_xor_b32_e32 v138, 0x20, v253
	ds_read_b64_tr_b16 v[138:139], v138
	v_xor_b32_e32 v140, 0x20, v252
	ds_read_b64_tr_b16 v[140:141], v140
	v_xor_b32_e32 v142, 0x40, v253
	ds_read_b64_tr_b16 v[142:143], v142
	v_xor_b32_e32 v144, 0x40, v252
	ds_read_b64_tr_b16 v[144:145], v144
	v_xor_b32_e32 v146, 0x60, v253
	ds_read_b64_tr_b16 v[146:147], v146
	v_xor_b32_e32 v148, 0x60, v252
	ds_read_b64_tr_b16 v[148:149], v148
	s_waitcnt lgkmcnt(0)
	v_mfma_f32_16x16x32_bf16 v[88:91], v[88:91], v[80:83], v[92:95]
	v_xor_b32_e32 v156, 0x80, v253
	ds_read_b64_tr_b16 v[92:93], v156
	v_mfma_f32_16x16x32_bf16 v[96:99], v[138:141], v[80:83], v[96:99]
	s_nop 0
	v_xor_b32_e32 v94, 0x80, v252
	ds_read_b64_tr_b16 v[94:95], v94
	v_xor_b32_e32 v138, 0xa0, v253
	v_mfma_f32_16x16x32_bf16 v[100:103], v[142:145], v[80:83], v[100:103]
	ds_read_b64_tr_b16 v[138:139], v138
	v_xor_b32_e32 v140, 0xa0, v252
	ds_read_b64_tr_b16 v[140:141], v140
	v_xor_b32_e32 v142, 0xc0, v253
	v_mfma_f32_16x16x32_bf16 v[126:129], v[146:149], v[80:83], v[126:129]
	ds_read_b64_tr_b16 v[142:143], v142
	v_xor_b32_e32 v144, 0xc0, v252
	ds_read_b64_tr_b16 v[144:145], v144
	v_xor_b32_e32 v146, 0xe0, v253
	ds_read_b64_tr_b16 v[146:147], v146
	v_xor_b32_e32 v148, 0xe0, v252
	ds_read_b64_tr_b16 v[148:149], v148
	s_waitcnt lgkmcnt(0)
	s_add_i32 s40, s40, s15
	v_mfma_f32_16x16x32_bf16 v[92:95], v[92:95], v[80:83], v[122:125]
	v_mfma_f32_16x16x32_bf16 v[122:125], v[138:141], v[80:83], v[130:133]
	v_mfma_f32_16x16x32_bf16 v[130:133], v[142:145], v[80:83], v[134:137]
	v_mfma_f32_16x16x32_bf16 v[80:83], v[146:149], v[80:83], v[84:87]
	s_nop 2
	v_add_u32_e32 v84, s40, v115
	v_add_u32_e32 v85, s40, v113
	v_lshlrev_b32_e32 v86, 2, v84
	v_and_b32_e32 v146, 12, v86
	v_bfe_u32 v147, v84, 2, 2
	v_lshl_add_u32 v148, v84, 8, v111
	v_lshlrev_b32_e32 v84, 2, v85
	v_and_b32_e32 v149, 12, v84
	v_bfe_u32 v150, v85, 2, 2
	v_bitop3_b32 v84, v146, v112, v147 bitop3:0x36
	v_lshl_add_u32 v151, v85, 8, v111
	v_lshl_add_u32 v253, v84, 4, v148
	v_bitop3_b32 v86, v149, v112, v150 bitop3:0x36
	ds_read_b64_tr_b16 v[84:85], v253
	v_lshl_add_u32 v252, v86, 4, v151
	ds_read_b64_tr_b16 v[86:87], v252
	v_xor_b32_e32 v134, 0x20, v253
	ds_read_b64_tr_b16 v[134:135], v134
	v_xor_b32_e32 v136, 0x20, v252
	ds_read_b64_tr_b16 v[136:137], v136
	v_xor_b32_e32 v138, 0x40, v253
	ds_read_b64_tr_b16 v[138:139], v138
	v_xor_b32_e32 v140, 0x40, v252
	ds_read_b64_tr_b16 v[140:141], v140
	v_xor_b32_e32 v142, 0x60, v253
	ds_read_b64_tr_b16 v[142:143], v142
	v_xor_b32_e32 v144, 0x60, v252
	ds_read_b64_tr_b16 v[144:145], v144
	s_waitcnt lgkmcnt(0)
	v_mfma_f32_16x16x32_bf16 v[84:87], v[84:87], v[76:79], v[88:91]
	v_xor_b32_e32 v152, 0x80, v253
	ds_read_b64_tr_b16 v[88:89], v152
	v_mfma_f32_16x16x32_bf16 v[96:99], v[134:137], v[76:79], v[96:99]
	s_nop 0
	v_xor_b32_e32 v90, 0x80, v252
	ds_read_b64_tr_b16 v[90:91], v90
	v_xor_b32_e32 v134, 0xa0, v253
	v_mfma_f32_16x16x32_bf16 v[100:103], v[138:141], v[76:79], v[100:103]
	ds_read_b64_tr_b16 v[134:135], v134
	v_xor_b32_e32 v136, 0xa0, v252
	ds_read_b64_tr_b16 v[136:137], v136
	v_xor_b32_e32 v138, 0xc0, v253
	v_mfma_f32_16x16x32_bf16 v[126:129], v[142:145], v[76:79], v[126:129]
	ds_read_b64_tr_b16 v[138:139], v138
	v_xor_b32_e32 v140, 0xc0, v252
	ds_read_b64_tr_b16 v[140:141], v140
	v_xor_b32_e32 v142, 0xe0, v253
	ds_read_b64_tr_b16 v[142:143], v142
	v_xor_b32_e32 v144, 0xe0, v252
	ds_read_b64_tr_b16 v[144:145], v144
	s_waitcnt lgkmcnt(0)
; __device__ __forceinline__ s16x4 tr_read_b64(unsigned addr) { s16x4 r; asm volatile("ds_read_b64_tr_b16 %0, %1" : "=v"(r) : "v"(addr) : "memory"); return r; }
; template <int L>
; __device__ __forceinline__ void layer_body(const Args& args, LAS unsigned char* lds, const int wave, const int G, const int gw, const int NGW, const int lo, const int hi,
;                                            unsigned char* const ws_kernel, const XcdBarrier& bar, int& pid) {
;     ...
;                     for (int s = 0; s < 8; ++s) {
;                         const int ir0 = (r0w - krlo + s) * 40 + coloff;
; #pragma unroll
;                         for (int mh = 0; mh < 2; ++mh) {
;                             s16x4 lo[4], hi[4];
; #pragma unroll
;                             for (int m4 = 0; m4 < 4; ++m4) { const int mt = mh * 4 + m4, r0_ = ir0 + 4 * kg + trq, r1_ = ir0 + 16 + 4 * kg + trq, ch_ = 2 * mt + (trp >> 1);
;                                 lo[m4] = tr_read_b64(IMG + vimg_off(r0_, ch_) + 8u * (trp & 1)); hi[m4] = tr_read_b64(IMG + vimg_off(r1_, ch_) + 8u * (trp & 1)); }
;                             asm volatile("s_waitcnt lgkmcnt(0)" ::: "memory"); __builtin_amdgcn_sched_barrier(0);
; #pragma unroll
;                             for (int m4 = 0; m4 < 4; ++m4) { const int mt = mh * 4 + m4; const bf16x8 va = (bf16x8){lo[m4][0], lo[m4][1], lo[m4][2], lo[m4][3], hi[m4][0], hi[m4][1], hi[m4][2], hi[m4][3]};
;                                 acc[mt] = __builtin_amdgcn_mfma_f32_16x16x32_bf16(va, pbf[s], acc[mt], 0, 0, 0); }
	s_add_i32 s41, s41, s15
	v_add_u32_e32 v115, s41, v115
	v_mfma_f32_16x16x32_bf16 v[88:91], v[88:91], v[76:79], v[92:95]
	v_add_u32_e32 v113, s41, v113
	v_bfe_u32 v147, v115, 2, 2
	v_lshl_add_u32 v148, v115, 8, v111
	v_lshlrev_b32_e32 v92, 2, v115
	v_and_b32_e32 v146, 12, v92
	v_lshlrev_b32_e32 v115, 2, v113
	v_mfma_f32_16x16x32_bf16 v[92:95], v[134:137], v[76:79], v[122:125]
	v_lshl_add_u32 v111, v113, 8, v111
	v_mfma_f32_16x16x32_bf16 v[122:125], v[138:141], v[76:79], v[130:133]
	v_and_b32_e32 v138, 12, v115
	v_bfe_u32 v139, v113, 2, 2
	v_mfma_f32_16x16x32_bf16 v[76:79], v[142:145], v[76:79], v[80:83]
	v_bitop3_b32 v130, v146, v116, v147 bitop3:0x36
	v_lshl_add_u32 v130, v130, 4, v148
	v_bitop3_b32 v116, v138, v116, v139 bitop3:0x36
	v_bitop3_b32 v80, v146, v112, v147 bitop3:0x36
	v_lshl_add_u32 v253, v80, 4, v148
	v_bitop3_b32 v82, v138, v112, v139 bitop3:0x36
	ds_read_b64_tr_b16 v[80:81], v253
	v_lshl_add_u32 v252, v82, 4, v111
	ds_read_b64_tr_b16 v[82:83], v252
	v_xor_b32_e32 v112, 0x20, v253
	ds_read_b64_tr_b16 v[112:113], v112
	v_xor_b32_e32 v114, 0x20, v252
	ds_read_b64_tr_b16 v[114:115], v114
	ds_read_b64_tr_b16 v[130:131], v130
	v_lshl_add_u32 v116, v116, 4, v111
	ds_read_b64_tr_b16 v[132:133], v116
	v_xor_b32_e32 v116, 0x60, v253
	ds_read_b64_tr_b16 v[134:135], v116
	v_xor_b32_e32 v116, 0x60, v252
	ds_read_b64_tr_b16 v[136:137], v116
	s_waitcnt lgkmcnt(0)
	v_mfma_f32_16x16x32_bf16 v[80:83], v[80:83], v[72:75], v[84:87]
	v_xor_b32_e32 v116, 0x80, v253
	ds_read_b64_tr_b16 v[84:85], v116
	v_mfma_f32_16x16x32_bf16 v[96:99], v[112:115], v[72:75], v[96:99]
	s_nop 0
	v_xor_b32_e32 v86, 0x80, v252
	ds_read_b64_tr_b16 v[86:87], v86
	v_xor_b32_e32 v112, 0xa0, v253
	ds_read_b64_tr_b16 v[112:113], v112
	v_xor_b32_e32 v114, 0xa0, v252
	v_mfma_f32_16x16x32_bf16 v[116:119], v[134:137], v[72:75], v[126:129]
	ds_read_b64_tr_b16 v[114:115], v114
	v_mfma_f32_16x16x32_bf16 v[100:103], v[130:133], v[72:75], v[100:103]
	s_nop 1
	v_xor_b32_e32 v126, 0xc0, v253
	ds_read_b64_tr_b16 v[126:127], v126
	v_xor_b32_e32 v120, 0xc0, v252
	ds_read_b64_tr_b16 v[128:129], v120
	v_xor_b32_e32 v120, 0xe0, v253
	ds_read_b64_tr_b16 v[130:131], v120
	v_xor_b32_e32 v111, 0xe0, v252
	ds_read_b64_tr_b16 v[132:133], v111
	s_waitcnt lgkmcnt(0)
; #define GAS __attribute__((address_space(1)))
; __device__ __forceinline__ unsigned pk2(float lo, float hi) { return f2bf(lo) | (f2bf(hi) << 16); }
; template <int L>
; __device__ __forceinline__ void layer_body(const Args& args, LAS unsigned char* lds, const int wave, const int G, const int gw, const int NGW, const int lo, const int hi,
;                                            unsigned char* const ws_kernel, const XcdBarrier& bar, int& pid) {
;     ...
;                     const float inv = 1.0f / sum;
;                     GAS bf16* op = (GAS bf16*)(obuf + (size_t)(b * SEQ + r * 64 + c) * D + h * HD + 4 * kg);
; #pragma unroll
;                     for (int mt = 0; mt < 8; ++mt) { v2u w; w.x = pk2(acc[mt][0] * inv, acc[mt][1] * inv); w.y = pk2(acc[mt][2] * inv, acc[mt][3] * inv); *(GAS v2u*)(op + 16 * mt) = w; }
;                     __syncthreads();
	v_div_scale_f32 v111, s[6:7], v104, v104, 1.0
	v_rcp_f32_e32 v120, v111
	v_mfma_f32_16x16x32_bf16 v[84:87], v[84:87], v[72:75], v[88:91]
	s_lshl_b32 s6, s14, 6
	s_add_i32 s6, s6, s60
	s_lshl_b32 s60, s36, 1
	v_fma_f32 v88, -v111, v120, 1.0
	v_fmac_f32_e32 v120, v88, v120
	v_mfma_f32_16x16x32_bf16 v[88:91], v[112:115], v[72:75], v[92:95]
	v_div_scale_f32 v112, vcc, 1.0, v104, 1.0
	v_mul_f32_e32 v113, v112, v120
	v_fma_f32 v114, -v111, v113, v112
	v_mfma_f32_16x16x32_bf16 v[92:95], v[126:129], v[72:75], v[122:125]
	v_fmac_f32_e32 v113, v114, v120
	v_fma_f32 v111, -v111, v113, v112
	s_add_i32 s84, s84, s82
	v_mfma_f32_16x16x32_bf16 v[72:75], v[130:133], v[72:75], v[76:79]
	s_add_i32 s96, s96, s92
	s_nop 1
	v_or_b32_e32 v78, s6, v109
	v_ashrrev_i32_e32 v79, 31, v78
	v_div_fmas_f32 v76, v111, v120, v113
	v_lshlrev_b64 v[78:79], 12, v[78:79]
	v_div_fixup_f32 v76, v76, v104, 1.0
	v_lshl_add_u64 v[78:79], s[4:5], 0, v[78:79]
	v_mov_b32_e32 v111, v82
	v_mov_b32_e32 v82, v81
	v_lshl_add_u64 v[78:79], v[78:79], 0, s[60:61]
	v_lshlrev_b32_e32 v104, 1, v110
	v_mov_b32_e32 v110, v80
	v_pk_mul_f32 v[80:81], v[76:77], v[82:83] op_sel_hi:[0,1]
	v_lshl_add_u64 v[78:79], v[78:79], 0, v[104:105]
	v_pk_mul_f32 v[110:111], v[76:77], v[110:111] op_sel_hi:[0,1]
	v_and_b32_sdwa v83, v81, v108 dst_sel:DWORD dst_unused:UNUSED_PAD src0_sel:WORD_1 src1_sel:DWORD
	v_and_b32_sdwa v77, v111, v108 dst_sel:DWORD dst_unused:UNUSED_PAD src0_sel:WORD_1 src1_sel:DWORD
	v_add3_u32 v81, v81, v83, s23
	v_add3_u32 v77, v111, v77, s23
	v_and_b32_e32 v81, 0xffff0000, v81
	v_or_b32_sdwa v81, v81, v77 dst_sel:DWORD dst_unused:UNUSED_PAD src0_sel:DWORD src1_sel:WORD_1
	v_cvt_pk_bf16_f32 v80, v110, v80
	global_store_dwordx2 v[78:79], v[80:81], off
	v_mov_b32_e32 v80, v96
	v_mov_b32_e32 v81, v98
	v_pk_mul_f32 v[80:81], v[76:77], v[80:81] op_sel_hi:[0,1]
	v_mov_b32_e32 v98, v97
	v_pk_mul_f32 v[82:83], v[76:77], v[98:99] op_sel_hi:[0,1]
	v_and_b32_sdwa v77, v81, v108 dst_sel:DWORD dst_unused:UNUSED_PAD src0_sel:WORD_1 src1_sel:DWORD
	v_add3_u32 v77, v81, v77, s23
	v_and_b32_sdwa v81, v83, v108 dst_sel:DWORD dst_unused:UNUSED_PAD src0_sel:WORD_1 src1_sel:DWORD
	v_add3_u32 v81, v83, v81, s23
	v_and_b32_e32 v81, 0xffff0000, v81
	v_or_b32_sdwa v81, v81, v77 dst_sel:DWORD dst_unused:UNUSED_PAD src0_sel:DWORD src1_sel:WORD_1
	v_cvt_pk_bf16_f32 v80, v80, v82
	global_store_dwordx2 v[78:79], v[80:81], off offset:32
	v_mov_b32_e32 v80, v100
	v_mov_b32_e32 v81, v102
	v_pk_mul_f32 v[80:81], v[76:77], v[80:81] op_sel_hi:[0,1]
	v_mov_b32_e32 v102, v101
	v_pk_mul_f32 v[82:83], v[76:77], v[102:103] op_sel_hi:[0,1]
	v_and_b32_sdwa v77, v81, v108 dst_sel:DWORD dst_unused:UNUSED_PAD src0_sel:WORD_1 src1_sel:DWORD
	v_add3_u32 v77, v81, v77, s23
	v_and_b32_sdwa v81, v83, v108 dst_sel:DWORD dst_unused:UNUSED_PAD src0_sel:WORD_1 src1_sel:DWORD
	v_add3_u32 v81, v83, v81, s23
	v_and_b32_e32 v81, 0xffff0000, v81
	v_or_b32_sdwa v81, v81, v77 dst_sel:DWORD dst_unused:UNUSED_PAD src0_sel:DWORD src1_sel:WORD_1
	v_cvt_pk_bf16_f32 v80, v80, v82
	global_store_dwordx2 v[78:79], v[80:81], off offset:64
	v_mov_b32_e32 v80, v116
	v_mov_b32_e32 v81, v118
	v_pk_mul_f32 v[80:81], v[76:77], v[80:81] op_sel_hi:[0,1]
	v_mov_b32_e32 v118, v117
	v_pk_mul_f32 v[82:83], v[76:77], v[118:119] op_sel_hi:[0,1]
	v_and_b32_sdwa v77, v81, v108 dst_sel:DWORD dst_unused:UNUSED_PAD src0_sel:WORD_1 src1_sel:DWORD
	v_add3_u32 v77, v81, v77, s23
	v_and_b32_sdwa v81, v83, v108 dst_sel:DWORD dst_unused:UNUSED_PAD src0_sel:WORD_1 src1_sel:DWORD
	v_add3_u32 v81, v83, v81, s23
	v_and_b32_e32 v81, 0xffff0000, v81
	v_or_b32_sdwa v81, v81, v77 dst_sel:DWORD dst_unused:UNUSED_PAD src0_sel:DWORD src1_sel:WORD_1
	v_cvt_pk_bf16_f32 v80, v80, v82
	global_store_dwordx2 v[78:79], v[80:81], off offset:96
	v_mov_b32_e32 v80, v84
	v_mov_b32_e32 v81, v86
	v_pk_mul_f32 v[80:81], v[76:77], v[80:81] op_sel_hi:[0,1]
	v_mov_b32_e32 v86, v85
	v_pk_mul_f32 v[82:83], v[76:77], v[86:87] op_sel_hi:[0,1]
	v_and_b32_sdwa v77, v81, v108 dst_sel:DWORD dst_unused:UNUSED_PAD src0_sel:WORD_1 src1_sel:DWORD
	v_add3_u32 v77, v81, v77, s23
	v_and_b32_sdwa v81, v83, v108 dst_sel:DWORD dst_unused:UNUSED_PAD src0_sel:WORD_1 src1_sel:DWORD
	v_add3_u32 v81, v83, v81, s23
	v_and_b32_e32 v81, 0xffff0000, v81
	v_or_b32_sdwa v81, v81, v77 dst_sel:DWORD dst_unused:UNUSED_PAD src0_sel:DWORD src1_sel:WORD_1
	v_cvt_pk_bf16_f32 v80, v80, v82
	global_store_dwordx2 v[78:79], v[80:81], off offset:128
	v_mov_b32_e32 v80, v88
	v_mov_b32_e32 v81, v90
	v_pk_mul_f32 v[80:81], v[76:77], v[80:81] op_sel_hi:[0,1]
	v_mov_b32_e32 v90, v89
	v_pk_mul_f32 v[82:83], v[76:77], v[90:91] op_sel_hi:[0,1]
	v_and_b32_sdwa v77, v81, v108 dst_sel:DWORD dst_unused:UNUSED_PAD src0_sel:WORD_1 src1_sel:DWORD
	v_add3_u32 v77, v81, v77, s23
	v_and_b32_sdwa v81, v83, v108 dst_sel:DWORD dst_unused:UNUSED_PAD src0_sel:WORD_1 src1_sel:DWORD
	v_add3_u32 v81, v83, v81, s23
	v_and_b32_e32 v81, 0xffff0000, v81
	v_or_b32_sdwa v81, v81, v77 dst_sel:DWORD dst_unused:UNUSED_PAD src0_sel:DWORD src1_sel:WORD_1
	v_cvt_pk_bf16_f32 v80, v80, v82
	global_store_dwordx2 v[78:79], v[80:81], off offset:160
	v_mov_b32_e32 v80, v92
	v_mov_b32_e32 v81, v94
	v_pk_mul_f32 v[80:81], v[76:77], v[80:81] op_sel_hi:[0,1]
	v_mov_b32_e32 v94, v93
	v_pk_mul_f32 v[82:83], v[76:77], v[94:95] op_sel_hi:[0,1]
	v_and_b32_sdwa v77, v81, v108 dst_sel:DWORD dst_unused:UNUSED_PAD src0_sel:WORD_1 src1_sel:DWORD
	v_add3_u32 v77, v81, v77, s23
	v_and_b32_sdwa v81, v83, v108 dst_sel:DWORD dst_unused:UNUSED_PAD src0_sel:WORD_1 src1_sel:DWORD
	v_add3_u32 v81, v83, v81, s23
	v_and_b32_e32 v81, 0xffff0000, v81
	v_or_b32_sdwa v81, v81, v77 dst_sel:DWORD dst_unused:UNUSED_PAD src0_sel:DWORD src1_sel:WORD_1
	v_cvt_pk_bf16_f32 v80, v80, v82
	global_store_dwordx2 v[78:79], v[80:81], off offset:192
	v_mov_b32_e32 v81, v74
	v_mov_b32_e32 v74, v73
	v_mov_b32_e32 v80, v72
	v_pk_mul_f32 v[72:73], v[76:77], v[74:75] op_sel_hi:[0,1]
	v_pk_mul_f32 v[80:81], v[76:77], v[80:81] op_sel_hi:[0,1]
	v_cvt_pk_bf16_f32 v73, v81, v73
	v_cvt_pk_bf16_f32 v72, v80, v72
	s_andn2_b64 vcc, exec, s[0:1]
	global_store_dwordx2 v[78:79], v[72:73], off offset:224
	s_barrier
	s_cbranch_vccz .LBB0_976

; template <int L>
; __device__ __forceinline__ void layer_body(const Args& args, LAS unsigned char* lds, const int wave, const int G, const int gw, const int NGW, const int lo, const int hi,
;                                            unsigned char* const ws_kernel, const XcdBarrier& bar, int& pid) {
;     ...
; #pragma unroll
;                         for (int j = 0; j < 4; ++j) { const int m = ms - 64 + 16 * T + 4 * kg + j, dd = m - mq; const bool valid = (m >= 0) && (m < Lc) && (dd >= -64) && (dd <= 64);
;                             sc[t][j] = valid ? a[j] * scale_log2 : -1e30f; }
.LBB0_1714:
	s_add_i32 s2, s83, s39
	v_or_b32_e32 v112, s2, v120
	v_sub_u32_e32 v136, v112, v121
	v_add_u32_e32 v136, 64, v136
	v_cmp_gt_i32_e32 vcc, s82, v112
	v_cmp_gt_u32_e64 s[2:3], s59, v136
	v_mul_f32_e32 v108, 0x3e0293ee, v108
	s_and_b64 vcc, vcc, s[2:3]
	v_or_b32_e32 v136, 1, v112
	v_cndmask_b32_e32 v108, v116, v108, vcc
	v_cmp_gt_i32_e32 vcc, s82, v136
	v_sub_u32_e32 v136, v136, v121
	v_add_u32_e32 v136, 64, v136
	v_cmp_gt_u32_e64 s[2:3], s59, v136
	v_mul_f32_e32 v109, 0x3e0293ee, v109
	s_and_b64 vcc, vcc, s[2:3]
	v_or_b32_e32 v136, 2, v112
	v_cndmask_b32_e32 v109, v116, v109, vcc
	v_cmp_gt_i32_e32 vcc, s82, v136
	v_sub_u32_e32 v136, v136, v121
	v_add_u32_e32 v136, 64, v136
	v_cmp_gt_u32_e64 s[2:3], s59, v136
	v_mul_f32_e32 v110, 0x3e0293ee, v110
	s_and_b64 vcc, vcc, s[2:3]
	v_or_b32_e32 v112, 3, v112
	v_cndmask_b32_e32 v110, v116, v110, vcc
	v_cmp_gt_i32_e32 vcc, s82, v112
	v_sub_u32_e32 v112, v112, v121
	v_add_u32_e32 v112, 64, v112
	v_cmp_gt_u32_e64 s[2:3], s59, v112
	s_and_b64 vcc, vcc, s[2:3]
	s_add_i32 s2, s83, s41
	v_or_b32_e32 v112, s2, v120
	v_sub_u32_e32 v136, v112, v121
	v_mul_f32_e32 v111, 0x3e0293ee, v111
	v_add_u32_e32 v136, 64, v136
	v_cndmask_b32_e32 v111, v116, v111, vcc
	v_cmp_gt_i32_e32 vcc, s82, v112
	v_cmp_gt_u32_e64 s[2:3], s59, v136
	v_mul_f32_e32 v104, 0x3e0293ee, v104
	s_and_b64 vcc, vcc, s[2:3]
	v_or_b32_e32 v136, 1, v112
	v_cndmask_b32_e32 v104, v116, v104, vcc
	v_cmp_gt_i32_e32 vcc, s82, v136
	v_sub_u32_e32 v136, v136, v121
	v_add_u32_e32 v136, 64, v136
	v_cmp_gt_u32_e64 s[2:3], s59, v136
	v_mul_f32_e32 v105, 0x3e0293ee, v105
	s_and_b64 vcc, vcc, s[2:3]
	v_or_b32_e32 v136, 2, v112
	v_cndmask_b32_e32 v105, v116, v105, vcc
	v_cmp_gt_i32_e32 vcc, s82, v136
	v_sub_u32_e32 v136, v136, v121
	v_add_u32_e32 v136, 64, v136
	v_cmp_gt_u32_e64 s[2:3], s59, v136
	v_mul_f32_e32 v106, 0x3e0293ee, v106
	s_and_b64 vcc, vcc, s[2:3]
	v_or_b32_e32 v112, 3, v112
	v_cndmask_b32_e32 v106, v116, v106, vcc
	v_cmp_gt_i32_e32 vcc, s82, v112
	v_sub_u32_e32 v112, v112, v121
	v_add_u32_e32 v112, 64, v112
	v_cmp_gt_u32_e64 s[2:3], s59, v112
	s_and_b64 vcc, vcc, s[2:3]
	s_add_i32 s2, s83, s43
	v_or_b32_e32 v112, s2, v120
	v_sub_u32_e32 v136, v112, v121
	v_mul_f32_e32 v107, 0x3e0293ee, v107
	v_add_u32_e32 v136, 64, v136
	v_cndmask_b32_e32 v107, v116, v107, vcc
	v_cmp_gt_i32_e32 vcc, s82, v112
	v_cmp_gt_u32_e64 s[2:3], s59, v136
	v_mul_f32_e32 v100, 0x3e0293ee, v100
	s_and_b64 vcc, vcc, s[2:3]
	v_or_b32_e32 v136, 1, v112
	v_cndmask_b32_e32 v100, v116, v100, vcc
	v_cmp_gt_i32_e32 vcc, s82, v136
	v_sub_u32_e32 v136, v136, v121
	v_add_u32_e32 v136, 64, v136
	v_cmp_gt_u32_e64 s[2:3], s59, v136
	v_mul_f32_e32 v101, 0x3e0293ee, v101
	s_and_b64 vcc, vcc, s[2:3]
	v_or_b32_e32 v136, 2, v112
	v_cndmask_b32_e32 v101, v116, v101, vcc
	v_cmp_gt_i32_e32 vcc, s82, v136
	v_sub_u32_e32 v136, v136, v121
	v_add_u32_e32 v136, 64, v136
	v_cmp_gt_u32_e64 s[2:3], s59, v136
	v_mul_f32_e32 v102, 0x3e0293ee, v102
	s_and_b64 vcc, vcc, s[2:3]
	v_or_b32_e32 v112, 3, v112
	v_cndmask_b32_e32 v102, v116, v102, vcc
	v_cmp_gt_i32_e32 vcc, s82, v112
	v_sub_u32_e32 v112, v112, v121
	v_add_u32_e32 v112, 64, v112
	v_cmp_gt_u32_e64 s[2:3], s59, v112
	s_and_b64 vcc, vcc, s[2:3]
	s_add_i32 s2, s83, s45
	v_or_b32_e32 v112, s2, v120
	v_sub_u32_e32 v136, v112, v121
	v_mul_f32_e32 v103, 0x3e0293ee, v103
	v_add_u32_e32 v136, 64, v136
	v_cndmask_b32_e32 v103, v116, v103, vcc
	v_cmp_gt_i32_e32 vcc, s82, v112
	v_cmp_gt_u32_e64 s[2:3], s59, v136
	v_mul_f32_e32 v96, 0x3e0293ee, v96
	s_and_b64 vcc, vcc, s[2:3]
	v_or_b32_e32 v136, 1, v112
	v_cndmask_b32_e32 v96, v116, v96, vcc
	v_cmp_gt_i32_e32 vcc, s82, v136
	v_sub_u32_e32 v136, v136, v121
	v_add_u32_e32 v136, 64, v136
	v_cmp_gt_u32_e64 s[2:3], s59, v136
	v_mul_f32_e32 v97, 0x3e0293ee, v97
	s_and_b64 vcc, vcc, s[2:3]
	v_or_b32_e32 v136, 2, v112
	v_cndmask_b32_e32 v97, v116, v97, vcc
	v_cmp_gt_i32_e32 vcc, s82, v136
	v_sub_u32_e32 v136, v136, v121
	v_add_u32_e32 v136, 64, v136
	v_cmp_gt_u32_e64 s[2:3], s59, v136
	v_mul_f32_e32 v98, 0x3e0293ee, v98
	s_and_b64 vcc, vcc, s[2:3]
	v_or_b32_e32 v112, 3, v112
	v_cndmask_b32_e32 v98, v116, v98, vcc
	v_cmp_gt_i32_e32 vcc, s82, v112
	v_sub_u32_e32 v112, v112, v121
	v_add_u32_e32 v112, 64, v112
	v_cmp_gt_u32_e64 s[2:3], s59, v112
	s_and_b64 vcc, vcc, s[2:3]
	s_add_i32 s2, s83, s47
	v_or_b32_e32 v112, s2, v120
	v_sub_u32_e32 v136, v112, v121
	v_mul_f32_e32 v99, 0x3e0293ee, v99
	v_add_u32_e32 v136, 64, v136
	v_cndmask_b32_e32 v99, v116, v99, vcc
	v_cmp_gt_i32_e32 vcc, s82, v112
	v_cmp_gt_u32_e64 s[2:3], s59, v136
	v_mul_f32_e32 v92, 0x3e0293ee, v92
	s_and_b64 vcc, vcc, s[2:3]
	v_or_b32_e32 v136, 1, v112
	v_cndmask_b32_e32 v92, v116, v92, vcc
	v_cmp_gt_i32_e32 vcc, s82, v136
	v_sub_u32_e32 v136, v136, v121
	v_add_u32_e32 v136, 64, v136
	v_cmp_gt_u32_e64 s[2:3], s59, v136
	v_mul_f32_e32 v93, 0x3e0293ee, v93
	s_and_b64 vcc, vcc, s[2:3]
	v_or_b32_e32 v136, 2, v112
	v_cndmask_b32_e32 v93, v116, v93, vcc
	v_cmp_gt_i32_e32 vcc, s82, v136
	v_sub_u32_e32 v136, v136, v121
	v_add_u32_e32 v136, 64, v136
	v_cmp_gt_u32_e64 s[2:3], s59, v136
	v_mul_f32_e32 v94, 0x3e0293ee, v94
	s_and_b64 vcc, vcc, s[2:3]
	v_or_b32_e32 v112, 3, v112
	v_cndmask_b32_e32 v94, v116, v94, vcc
	v_cmp_gt_i32_e32 vcc, s82, v112
	v_sub_u32_e32 v112, v112, v121
	v_add_u32_e32 v112, 64, v112
	s_add_i32 s83, s83, s49
	v_cmp_gt_u32_e64 s[2:3], s59, v112
	v_or_b32_e32 v112, s83, v120
	v_sub_u32_e32 v136, v112, v121
	v_mul_f32_e32 v95, 0x3e0293ee, v95
	s_and_b64 vcc, vcc, s[2:3]
	v_add_u32_e32 v136, 64, v136
	v_cndmask_b32_e32 v95, v116, v95, vcc
	v_cmp_gt_i32_e32 vcc, s82, v112
	v_cmp_gt_u32_e64 s[2:3], s59, v136
	v_mul_f32_e32 v88, 0x3e0293ee, v88
; __device__ __forceinline__ unsigned pk2(float lo, float hi) { return f2bf(lo) | (f2bf(hi) << 16); }
; template <int L>
; __device__ __forceinline__ void layer_body(const Args& args, LAS unsigned char* lds, const int wave, const int G, const int gw, const int NGW, const int lo, const int hi,
;                                            unsigned char* const ws_kernel, const XcdBarrier& bar, int& pid) {
;     ...
;                         for (int j = 0; j < 4; ++j) { const int m = ms - 64 + 16 * T + 4 * kg + j, dd = m - mq; const bool valid = (m >= 0) && (m < Lc) && (dd >= -64) && (dd <= 64);
;                             sc[t][j] = valid ? a[j] * scale_log2 : -1e30f; }
;                         __builtin_amdgcn_sched_barrier(0);
;                     }
;                     if (unit + GH < UEND) DSW_LOADQ(unit + GH);
;                     float mx = -1e30f;
; #pragma unroll
;                     for (int t = 0; t < 10; ++t)
; #pragma unroll
;                         for (int j = 0; j < 4; ++j) mx = fmaxf(mx, sc[t][j]);
;                     mx = fmaxf(mx, __shfl_xor(mx, 16)); mx = fmaxf(mx, __shfl_xor(mx, 32));
;                     float sum = 0.f;
; #pragma unroll
;                     for (int t = 0; t < 10; ++t)
; #pragma unroll
;                         for (int j = 0; j < 4; ++j) { sc[t][j] = __builtin_amdgcn_exp2f(sc[t][j] - mx); sum += sc[t][j]; }
;                     sum += __shfl_xor(sum, 16); sum += __shfl_xor(sum, 32);
;                     f32x4 acc[8];
; #pragma unroll
;                     for (int mt = 0; mt < 8; ++mt) acc[mt] = (f32x4){0.f, 0.f, 0.f, 0.f};
;                     const int trq = (lane & 15) >> 2, trp = lane & 3;
; #pragma unroll
;                     for (int s = 0; s < 5; ++s) {
;                         const int T0 = min(wave + 2 * s, 15), T1 = min(wave + 2 * s + 1, 15);
;                         bf16x8 pb; { const f32x4 p0 = sc[2 * s], p1 = sc[2 * s + 1]; v4u w; w.x = pk2(p0[0], p0[1]); w.y = pk2(p0[2], p0[3]); w.z = pk2(p1[0], p1[1]); w.w = pk2(p1[2], p1[3]); pb = __builtin_bit_cast(bf16x8, w); }
; #pragma unroll
;                         for (int mh = 0; mh < 2; ++mh) {
;                             s16x4 lo[4], hi[4];
; #pragma unroll
;                             for (int m4 = 0; m4 < 4; ++m4) { const int mt = mh * 4 + m4, r0_ = 16 * T0 + 4 * kg + trq, r1_ = 16 * T1 + 4 * kg + trq, ch_ = 2 * mt + (trp >> 1);
	s_and_b64 vcc, vcc, s[2:3]
	v_cndmask_b32_e32 v136, v116, v88, vcc
	v_or_b32_e32 v88, 1, v112
	v_cmp_gt_i32_e32 vcc, s82, v88
	v_sub_u32_e32 v88, v88, v121
	v_add_u32_e32 v88, 64, v88
	v_cmp_gt_u32_e64 s[2:3], s59, v88
	v_mul_f32_e32 v88, 0x3e0293ee, v89
	s_and_b64 vcc, vcc, s[2:3]
	v_cndmask_b32_e32 v89, v116, v88, vcc
	v_or_b32_e32 v88, 2, v112
	v_cmp_gt_i32_e32 vcc, s82, v88
	v_sub_u32_e32 v88, v88, v121
	v_add_u32_e32 v88, 64, v88
	v_cmp_gt_u32_e64 s[2:3], s59, v88
	v_mul_f32_e32 v88, 0x3e0293ee, v90
	s_and_b64 vcc, vcc, s[2:3]
	v_cndmask_b32_e32 v137, v116, v88, vcc
	v_or_b32_e32 v88, 3, v112
	v_cmp_gt_i32_e32 vcc, s82, v88
	v_sub_u32_e32 v88, v88, v121
	v_add_u32_e32 v88, 64, v88
	v_cmp_gt_u32_e64 s[2:3], s59, v88
	v_mul_f32_e32 v88, 0x3e0293ee, v91
	s_and_b64 vcc, vcc, s[2:3]
	v_cndmask_b32_e32 v112, v116, v88, vcc
	v_sub_u32_e32 v88, v135, v121
	v_cmp_gt_i32_e32 vcc, s82, v135
	v_add_u32_e32 v88, 64, v88
	v_cmp_gt_u32_e64 s[2:3], s59, v88
	s_and_b64 s[4:5], s[76:77], vcc
	v_mul_f32_e32 v86, 0x3e0293ee, v86
	s_and_b64 vcc, s[4:5], s[2:3]
	v_sub_u32_e32 v88, v133, v121
	v_cndmask_b32_e32 v86, v116, v86, vcc
	v_cmp_gt_i32_e32 vcc, s82, v133
	v_add_u32_e32 v88, 64, v88
	v_cmp_gt_u32_e64 s[2:3], s59, v88
	s_and_b64 s[4:5], s[74:75], vcc
	v_mul_f32_e32 v84, 0x3e0293ee, v84
	s_and_b64 vcc, s[4:5], s[2:3]
	v_cndmask_b32_e32 v88, v116, v84, vcc
	v_sub_u32_e32 v84, v129, v121
	v_cmp_gt_i32_e32 vcc, s82, v129
	v_add_u32_e32 v84, 64, v84
	v_cmp_gt_u32_e64 s[2:3], s59, v84
	s_and_b64 s[4:5], s[72:73], vcc
	v_mul_f32_e32 v82, 0x3e0293ee, v82
	s_and_b64 vcc, s[4:5], s[2:3]
	v_cndmask_b32_e32 v90, v116, v82, vcc
	v_sub_u32_e32 v82, v127, v121
	v_cmp_gt_i32_e32 vcc, s82, v127
	v_add_u32_e32 v82, 64, v82
	v_cmp_gt_u32_e64 s[2:3], s59, v82
	s_and_b64 s[4:5], s[70:71], vcc
	v_mul_f32_e32 v80, 0x3e0293ee, v80
	s_and_b64 vcc, s[4:5], s[2:3]
	v_cndmask_b32_e32 v91, v116, v80, vcc
	s_mov_b32 s2, 0xf149f2ca
	v_max3_f32 v80, v91, s2, v125
	v_max3_f32 v80, v80, v124, v126
	v_max3_f32 v80, v80, v90, v81
	v_max3_f32 v80, v80, v128, v83
	v_max3_f32 v80, v80, v88, v131
	v_max3_f32 v80, v80, v130, v132
	v_max3_f32 v80, v80, v86, v85
	v_max3_f32 v80, v80, v134, v87
	v_max3_f32 v80, v80, v108, v109
	v_max3_f32 v80, v80, v110, v111
	v_max3_f32 v80, v80, v104, v105
	v_max3_f32 v80, v80, v106, v107
	v_max3_f32 v80, v80, v100, v101
	v_max3_f32 v80, v80, v102, v103
	v_max3_f32 v80, v80, v96, v97
	v_max3_f32 v80, v80, v98, v99
	v_max3_f32 v80, v80, v92, v93
	v_max3_f32 v80, v80, v94, v95
	v_max3_f32 v80, v80, v136, v89
	v_and_b32_e32 v84, 64, v115
	v_max3_f32 v82, v80, v137, v112
	v_xor_b32_e32 v80, 16, v115
	v_add_u32_e32 v84, 64, v84
	v_cmp_lt_i32_e32 vcc, v80, v84
	s_sub_i32 s2, 4, s67
	s_and_b32 s4, s12, 15
	v_cndmask_b32_e32 v80, v115, v80, vcc
	v_lshlrev_b32_e32 v80, 2, v80
	ds_bpermute_b32 v127, v80, v82
	s_lshr_b32 s2, s81, s2
	s_waitcnt lgkmcnt(0)
	v_max_f32_e32 v127, v127, v127
	v_max_f32_e32 v82, v82, v127
	v_xor_b32_e32 v127, 32, v115
	v_cmp_lt_i32_e32 vcc, v127, v84
	s_nop 1
	v_cndmask_b32_e32 v84, v115, v127, vcc
	v_lshlrev_b32_e32 v84, 2, v84
	ds_bpermute_b32 v127, v84, v82
	s_waitcnt lgkmcnt(0)
	v_max_f32_e32 v127, v127, v127
	v_max_f32_e32 v82, v82, v127
	v_sub_f32_e32 v81, v81, v82
	v_exp_f32_e32 v133, v81
	v_sub_f32_e32 v81, v128, v82
	v_exp_f32_e32 v128, v81
	v_sub_f32_e32 v81, v83, v82
	v_exp_f32_e32 v135, v81
	v_sub_f32_e32 v81, v88, v82
	v_exp_f32_e32 v150, v81
	v_sub_f32_e32 v81, v131, v82
	v_exp_f32_e32 v151, v81
	v_sub_f32_e32 v81, v130, v82
	v_exp_f32_e32 v152, v81
	v_sub_f32_e32 v81, v132, v82
	v_exp_f32_e32 v153, v81
	v_sub_f32_e32 v81, v86, v82
	v_exp_f32_e32 v154, v81
	v_sub_f32_e32 v81, v85, v82
	v_exp_f32_e32 v155, v81
	v_sub_f32_e32 v81, v134, v82
	v_exp_f32_e32 v156, v81
	v_sub_f32_e32 v81, v87, v82
	v_exp_f32_e32 v157, v81
	v_sub_f32_e32 v81, v108, v82
	v_exp_f32_e32 v166, v81
	v_sub_f32_e32 v81, v109, v82
	v_exp_f32_e32 v167, v81
	v_sub_f32_e32 v81, v110, v82
	v_exp_f32_e32 v110, v81
	v_sub_f32_e32 v81, v111, v82
	v_sub_f32_e32 v91, v91, v82
	v_exp_f32_e32 v111, v81
	v_sub_f32_e32 v81, v104, v82
	v_exp_f32_e32 v127, v91
	v_sub_f32_e32 v91, v125, v82
	v_exp_f32_e32 v168, v81
	v_sub_f32_e32 v81, v105, v82
	v_exp_f32_e32 v125, v91
	v_sub_f32_e32 v91, v124, v82
	v_exp_f32_e32 v169, v81
	v_sub_f32_e32 v81, v106, v82
	v_exp_f32_e32 v124, v91
	v_sub_f32_e32 v91, v126, v82
	v_exp_f32_e32 v170, v81
	v_sub_f32_e32 v81, v107, v82
	v_sub_f32_e32 v83, v93, v82
	v_exp_f32_e32 v126, v91
	v_sub_f32_e32 v90, v90, v82
	v_exp_f32_e32 v171, v81
	v_sub_f32_e32 v81, v100, v82
	v_exp_f32_e32 v88, v83
	v_sub_f32_e32 v83, v94, v82
	v_exp_f32_e32 v129, v90
	v_exp_f32_e32 v172, v81
	v_sub_f32_e32 v81, v101, v82
	v_exp_f32_e32 v85, v83
	v_sub_f32_e32 v83, v95, v82
	v_add_f32_e32 v95, 0, v127
	v_exp_f32_e32 v173, v81
	v_sub_f32_e32 v81, v102, v82
	v_add_f32_e32 v95, v125, v95
	v_exp_f32_e32 v174, v81
	v_sub_f32_e32 v81, v103, v82
	v_add_f32_e32 v95, v124, v95
	v_exp_f32_e32 v175, v81
	v_sub_f32_e32 v81, v96, v82
	v_exp_f32_e32 v90, v83
	v_sub_f32_e32 v83, v136, v82
	v_add_f32_e32 v95, v126, v95
	v_exp_f32_e32 v176, v81
	v_sub_f32_e32 v81, v97, v82
	v_exp_f32_e32 v87, v83
	v_sub_f32_e32 v83, v89, v82
	v_add_f32_e32 v95, v129, v95
	v_exp_f32_e32 v177, v81
	v_sub_f32_e32 v81, v98, v82
	v_exp_f32_e32 v91, v83
	v_sub_f32_e32 v83, v137, v82
	v_add_f32_e32 v95, v133, v95
	v_exp_f32_e32 v178, v81
	v_sub_f32_e32 v81, v99, v82
	v_exp_f32_e32 v89, v83
	v_sub_f32_e32 v83, v112, v82
	v_add_f32_e32 v95, v128, v95
	v_exp_f32_e32 v179, v81
	v_sub_f32_e32 v81, v92, v82
	v_exp_f32_e32 v92, v83
	v_lshrrev_b32_e32 v83, 2, v123
	v_add_f32_e32 v158, v135, v95
	v_or_b32_e32 v93, v120, v83
	v_bfe_u32 v112, v122, 1, 1
	v_and_b32_e32 v94, 12, v122
	v_lshlrev_b32_e32 v86, 3, v122
	v_and_or_b32 v86, v86, 8, s55
	v_cvt_pk_bf16_f32 v105, v128, v135
	v_cvt_pk_bf16_f32 v103, v124, v126
	v_or3_b32 v95, s14, v83, v120
	v_lshl_or_b32 v97, v93, 8, v117
	v_bitop3_b32 v93, v119, v112, v94 bitop3:0x36
	v_cvt_pk_bf16_f32 v102, v127, v125
	v_lshl_add_u32 v147, v95, 8, v86
	v_lshlrev_b32_e32 v98, 4, v93
	v_add3_u32 v148, v86, s50, v97
	v_add_u32_e32 v93, v147, v98
	v_or_b32_e32 v146, v119, v94
	ds_read_b64_tr_b16 v[106:107], v93
	v_add_u32_e32 v93, v148, v98
	ds_read_b64_tr_b16 v[108:109], v93
	v_bitop3_b32 v93, v112, v146, 2 bitop3:0x36
	v_lshlrev_b32_e32 v99, 4, v93
	v_add_u32_e32 v93, v147, v99
	ds_read_b64_tr_b16 v[122:123], v93
	v_add_u32_e32 v93, v148, v99
	ds_read_b64_tr_b16 v[124:125], v93
	v_bitop3_b32 v93, v112, v146, 4 bitop3:0x36
	v_lshlrev_b32_e32 v100, 4, v93
	v_add_u32_e32 v93, v147, v100
	ds_read_b64_tr_b16 v[126:127], v93
	v_add_u32_e32 v93, v148, v100
	v_cvt_pk_bf16_f32 v104, v129, v133
	ds_read_b64_tr_b16 v[128:129], v93
	v_bitop3_b32 v93, v112, v146, 6 bitop3:0x36
	v_lshlrev_b32_e32 v101, 4, v93
	v_add_u32_e32 v93, v147, v101
	ds_read_b64_tr_b16 v[130:131], v93
	v_exp_f32_e32 v81, v81
	v_add_u32_e32 v93, v148, v101
	ds_read_b64_tr_b16 v[132:133], v93
	s_waitcnt lgkmcnt(0)
; __device__ __forceinline__ unsigned pk2(float lo, float hi) { return f2bf(lo) | (f2bf(hi) << 16); }
; __device__ __forceinline__ s16x4 tr_read_b64(unsigned addr) { s16x4 r; asm volatile("ds_read_b64_tr_b16 %0, %1" : "=v"(r) : "v"(addr) : "memory"); return r; }
; template <int L>
; __device__ __forceinline__ void layer_body(const Args& args, LAS unsigned char* lds, const int wave, const int G, const int gw, const int NGW, const int lo, const int hi,
;                                            unsigned char* const ws_kernel, const XcdBarrier& bar, int& pid) {
;     ...
; #pragma unroll
;                     for (int s = 0; s < 5; ++s) {
;                         const int T0 = min(wave + 2 * s, 15), T1 = min(wave + 2 * s + 1, 15);
;                         bf16x8 pb; { const f32x4 p0 = sc[2 * s], p1 = sc[2 * s + 1]; v4u w; w.x = pk2(p0[0], p0[1]); w.y = pk2(p0[2], p0[3]); w.z = pk2(p1[0], p1[1]); w.w = pk2(p1[2], p1[3]); pb = __builtin_bit_cast(bf16x8, w); }
; #pragma unroll
;                         for (int mh = 0; mh < 2; ++mh) {
;                             s16x4 lo[4], hi[4];
; #pragma unroll
;                             for (int m4 = 0; m4 < 4; ++m4) { const int mt = mh * 4 + m4, r0_ = 16 * T0 + 4 * kg + trq, r1_ = 16 * T1 + 4 * kg + trq, ch_ = 2 * mt + (trp >> 1);
;                                 lo[m4] = tr_read_b64(Vimg + vimg_off(r0_, ch_) + 8u * (trp & 1)); hi[m4] = tr_read_b64(Vimg + vimg_off(r1_, ch_) + 8u * (trp & 1)); }
;                             asm volatile("s_waitcnt lgkmcnt(0)" ::: "memory"); __builtin_amdgcn_sched_barrier(0);
; #pragma unroll
;                             for (int m4 = 0; m4 < 4; ++m4) { const int mt = mh * 4 + m4; const bf16x8 va = (bf16x8){lo[m4][0], lo[m4][1], lo[m4][2], lo[m4][3], hi[m4][0], hi[m4][1], hi[m4][2], hi[m4][3]};
;                                 acc[mt] = __builtin_amdgcn_mfma_f32_16x16x32_bf16(va, pb, acc[mt], 0, 0, 0); }
	v_bitop3_b32 v93, v112, v146, 8 bitop3:0x36
	v_lshlrev_b32_e32 v94, 4, v93
	v_add_u32_e32 v93, v147, v94
	ds_read_b64_tr_b16 v[134:135], v93
	v_add_u32_e32 v93, v148, v94
	ds_read_b64_tr_b16 v[136:137], v93
	v_bitop3_b32 v93, v112, v146, 10 bitop3:0x36
	v_lshlrev_b32_e32 v95, 4, v93
	v_add_u32_e32 v93, v147, v95
	ds_read_b64_tr_b16 v[138:139], v93
	v_add_u32_e32 v93, v148, v95
	ds_read_b64_tr_b16 v[140:141], v93
	v_bitop3_b32 v93, v112, v146, 12 bitop3:0x36
	v_lshlrev_b32_e32 v96, 4, v93
	v_add_u32_e32 v93, v147, v96
	ds_read_b64_tr_b16 v[142:143], v93
	v_add_u32_e32 v93, v148, v96
	ds_read_b64_tr_b16 v[144:145], v93
	v_bitop3_b32 v93, v112, v146, 14 bitop3:0x36
	v_lshlrev_b32_e32 v93, 4, v93
	v_add_u32_e32 v112, v147, v93
	ds_read_b64_tr_b16 v[146:147], v112
	v_add_u32_e32 v112, v148, v93
	ds_read_b64_tr_b16 v[148:149], v112
	s_waitcnt lgkmcnt(0)
	v_mfma_f32_16x16x32_bf16 v[106:109], v[106:109], v[102:105], 0
	v_mfma_f32_16x16x32_bf16 v[122:125], v[122:125], v[102:105], 0
	v_mfma_f32_16x16x32_bf16 v[126:129], v[126:129], v[102:105], 0
	v_mfma_f32_16x16x32_bf16 v[130:133], v[130:133], v[102:105], 0
	v_add_f32_e32 v112, v150, v158
	v_add_f32_e32 v112, v151, v112
	v_mfma_f32_16x16x32_bf16 v[134:137], v[134:137], v[102:105], 0
	v_add_f32_e32 v112, v152, v112
	v_add_f32_e32 v112, v153, v112
	v_add_f32_e32 v112, v154, v112
	v_mfma_f32_16x16x32_bf16 v[138:141], v[138:141], v[102:105], 0
	v_add_f32_e32 v112, v155, v112
	v_mfma_f32_16x16x32_bf16 v[142:145], v[142:145], v[102:105], 0
	v_add_f32_e32 v112, v156, v112
	v_add_f32_e32 v112, v157, v112
	v_mfma_f32_16x16x32_bf16 v[102:105], v[146:149], v[102:105], 0
	v_cvt_pk_bf16_f32 v146, v150, v151
	v_or3_b32 v150, s22, v83, v120
	v_lshl_add_u32 v180, v150, 8, v86
	v_add3_u32 v181, v86, s51, v97
	v_add_u32_e32 v150, v180, v98
	v_cvt_pk_bf16_f32 v148, v154, v155
	v_cvt_pk_bf16_f32 v147, v152, v153
	ds_read_b64_tr_b16 v[150:151], v150
	v_add_u32_e32 v152, v181, v98
	v_cvt_pk_bf16_f32 v149, v156, v157
	ds_read_b64_tr_b16 v[152:153], v152
	v_add_u32_e32 v154, v180, v99
	ds_read_b64_tr_b16 v[154:155], v154
	v_add_u32_e32 v156, v181, v99
	ds_read_b64_tr_b16 v[156:157], v156
	v_add_u32_e32 v158, v180, v100
	ds_read_b64_tr_b16 v[158:159], v158
	v_add_u32_e32 v160, v181, v100
	ds_read_b64_tr_b16 v[160:161], v160
	v_add_u32_e32 v162, v180, v101
	ds_read_b64_tr_b16 v[162:163], v162
	v_add_u32_e32 v164, v181, v101
	ds_read_b64_tr_b16 v[164:165], v164
	s_waitcnt lgkmcnt(0)
	v_mfma_f32_16x16x32_bf16 v[106:109], v[150:153], v[146:149], v[106:109]
	v_add_u32_e32 v150, v180, v94
	ds_read_b64_tr_b16 v[150:151], v150
	v_add_u32_e32 v152, v181, v94
	v_mfma_f32_16x16x32_bf16 v[122:125], v[154:157], v[146:149], v[122:125]
	ds_read_b64_tr_b16 v[152:153], v152
	v_add_u32_e32 v154, v180, v95
	ds_read_b64_tr_b16 v[154:155], v154
	v_add_u32_e32 v156, v181, v95
	v_mfma_f32_16x16x32_bf16 v[126:129], v[158:161], v[146:149], v[126:129]
	ds_read_b64_tr_b16 v[156:157], v156
	v_add_u32_e32 v158, v180, v96
	ds_read_b64_tr_b16 v[158:159], v158
	v_add_u32_e32 v160, v181, v96
	v_mfma_f32_16x16x32_bf16 v[130:133], v[162:165], v[146:149], v[130:133]
	ds_read_b64_tr_b16 v[160:161], v160
	v_add_u32_e32 v162, v180, v93
	ds_read_b64_tr_b16 v[162:163], v162
	v_add_u32_e32 v164, v181, v93
	ds_read_b64_tr_b16 v[164:165], v164
	s_waitcnt lgkmcnt(0)
	v_add_f32_e32 v112, v166, v112
	v_add_f32_e32 v112, v167, v112
	v_mfma_f32_16x16x32_bf16 v[134:137], v[150:153], v[146:149], v[134:137]
	v_add_f32_e32 v112, v110, v112
	v_add_f32_e32 v112, v111, v112
	v_mfma_f32_16x16x32_bf16 v[138:141], v[154:157], v[146:149], v[138:141]
	v_mfma_f32_16x16x32_bf16 v[142:145], v[158:161], v[146:149], v[142:145]
	v_add_f32_e32 v112, v168, v112
	v_add_f32_e32 v112, v169, v112
	v_add_f32_e32 v112, v170, v112
	v_mfma_f32_16x16x32_bf16 v[102:105], v[162:165], v[146:149], v[102:105]
	v_cvt_pk_bf16_f32 v149, v170, v171
	v_cvt_pk_bf16_f32 v148, v168, v169
	v_cvt_pk_bf16_f32 v147, v110, v111
	v_or3_b32 v110, s38, v83, v120
	v_lshl_add_u32 v110, v110, 8, v86
	v_cvt_pk_bf16_f32 v146, v166, v167
	v_add3_u32 v111, v86, s52, v97
	v_add_u32_e32 v150, v110, v98
	ds_read_b64_tr_b16 v[150:151], v150
	v_add_u32_e32 v152, v111, v98
	ds_read_b64_tr_b16 v[152:153], v152
	v_add_u32_e32 v154, v110, v99
	ds_read_b64_tr_b16 v[154:155], v154
	v_add_u32_e32 v156, v111, v99
	ds_read_b64_tr_b16 v[156:157], v156
	v_add_u32_e32 v158, v110, v100
	ds_read_b64_tr_b16 v[158:159], v158
	v_add_u32_e32 v160, v111, v100
	ds_read_b64_tr_b16 v[160:161], v160
	v_add_u32_e32 v162, v110, v101
	ds_read_b64_tr_b16 v[162:163], v162
	v_add_u32_e32 v164, v111, v101
	ds_read_b64_tr_b16 v[164:165], v164
	s_waitcnt lgkmcnt(0)
	v_add_f32_e32 v112, v171, v112
	v_mfma_f32_16x16x32_bf16 v[106:109], v[150:153], v[146:149], v[106:109]
	v_add_u32_e32 v150, v110, v94
	ds_read_b64_tr_b16 v[150:151], v150
	v_add_u32_e32 v152, v111, v94
	v_mfma_f32_16x16x32_bf16 v[122:125], v[154:157], v[146:149], v[122:125]
	ds_read_b64_tr_b16 v[152:153], v152
	v_add_u32_e32 v154, v110, v95
	ds_read_b64_tr_b16 v[154:155], v154
	v_add_u32_e32 v156, v111, v95
	v_mfma_f32_16x16x32_bf16 v[126:129], v[158:161], v[146:149], v[126:129]
	ds_read_b64_tr_b16 v[156:157], v156
	v_add_u32_e32 v158, v110, v96
	ds_read_b64_tr_b16 v[158:159], v158
	v_add_u32_e32 v160, v111, v96
	ds_read_b64_tr_b16 v[160:161], v160
	v_mfma_f32_16x16x32_bf16 v[130:133], v[162:165], v[146:149], v[130:133]
	v_add_u32_e32 v110, v110, v93
	ds_read_b64_tr_b16 v[162:163], v110
	v_add_u32_e32 v110, v111, v93
	ds_read_b64_tr_b16 v[164:165], v110
	s_waitcnt lgkmcnt(0)
; __device__ __forceinline__ unsigned pk2(float lo, float hi) { return f2bf(lo) | (f2bf(hi) << 16); }
; __device__ __forceinline__ s16x4 tr_read_b64(unsigned addr) { s16x4 r; asm volatile("ds_read_b64_tr_b16 %0, %1" : "=v"(r) : "v"(addr) : "memory"); return r; }
; template <int L>
; __device__ __forceinline__ void layer_body(const Args& args, LAS unsigned char* lds, const int wave, const int G, const int gw, const int NGW, const int lo, const int hi,
;                                            unsigned char* const ws_kernel, const XcdBarrier& bar, int& pid) {
;     ...
;                     for (int t = 0; t < 10; ++t)
; #pragma unroll
;                         for (int j = 0; j < 4; ++j) { sc[t][j] = __builtin_amdgcn_exp2f(sc[t][j] - mx); sum += sc[t][j]; }
;                     sum += __shfl_xor(sum, 16); sum += __shfl_xor(sum, 32);
;                     f32x4 acc[8];
; #pragma unroll
;                     for (int mt = 0; mt < 8; ++mt) acc[mt] = (f32x4){0.f, 0.f, 0.f, 0.f};
;                     const int trq = (lane & 15) >> 2, trp = lane & 3;
; #pragma unroll
;                     for (int s = 0; s < 5; ++s) {
;                         const int T0 = min(wave + 2 * s, 15), T1 = min(wave + 2 * s + 1, 15);
;                         bf16x8 pb; { const f32x4 p0 = sc[2 * s], p1 = sc[2 * s + 1]; v4u w; w.x = pk2(p0[0], p0[1]); w.y = pk2(p0[2], p0[3]); w.z = pk2(p1[0], p1[1]); w.w = pk2(p1[2], p1[3]); pb = __builtin_bit_cast(bf16x8, w); }
; #pragma unroll
;                         for (int mh = 0; mh < 2; ++mh) {
;                             s16x4 lo[4], hi[4];
; #pragma unroll
;                             for (int m4 = 0; m4 < 4; ++m4) { const int mt = mh * 4 + m4, r0_ = 16 * T0 + 4 * kg + trq, r1_ = 16 * T1 + 4 * kg + trq, ch_ = 2 * mt + (trp >> 1);
;                                 lo[m4] = tr_read_b64(Vimg + vimg_off(r0_, ch_) + 8u * (trp & 1)); hi[m4] = tr_read_b64(Vimg + vimg_off(r1_, ch_) + 8u * (trp & 1)); }
;                             asm volatile("s_waitcnt lgkmcnt(0)" ::: "memory"); __builtin_amdgcn_sched_barrier(0);
; #pragma unroll
;                             for (int m4 = 0; m4 < 4; ++m4) { const int mt = mh * 4 + m4; const bf16x8 va = (bf16x8){lo[m4][0], lo[m4][1], lo[m4][2], lo[m4][3], hi[m4][0], hi[m4][1], hi[m4][2], hi[m4][3]};
;                                 acc[mt] = __builtin_amdgcn_mfma_f32_16x16x32_bf16(va, pb, acc[mt], 0, 0, 0); }
	v_mfma_f32_16x16x32_bf16 v[134:137], v[150:153], v[146:149], v[134:137]
	v_mfma_f32_16x16x32_bf16 v[138:141], v[154:157], v[146:149], v[138:141]
	v_add_f32_e32 v110, v172, v112
	v_mfma_f32_16x16x32_bf16 v[142:145], v[158:161], v[146:149], v[142:145]
	v_add_f32_e32 v110, v173, v110
	v_mfma_f32_16x16x32_bf16 v[102:105], v[162:165], v[146:149], v[102:105]
	v_cvt_pk_bf16_f32 v149, v178, v179
	v_or3_b32 v111, s42, v83, v120
	v_lshl_add_u32 v111, v111, 8, v86
	v_cvt_pk_bf16_f32 v148, v176, v177
	v_add3_u32 v112, v86, s53, v97
	v_add_u32_e32 v150, v111, v98
	v_cvt_pk_bf16_f32 v146, v172, v173
	ds_read_b64_tr_b16 v[150:151], v150
	v_add_u32_e32 v152, v112, v98
	v_cvt_pk_bf16_f32 v147, v174, v175
	ds_read_b64_tr_b16 v[152:153], v152
	v_add_u32_e32 v154, v111, v99
	ds_read_b64_tr_b16 v[154:155], v154
	v_add_u32_e32 v156, v112, v99
	ds_read_b64_tr_b16 v[156:157], v156
	v_add_u32_e32 v158, v111, v100
	ds_read_b64_tr_b16 v[158:159], v158
	v_add_u32_e32 v160, v112, v100
	ds_read_b64_tr_b16 v[160:161], v160
	v_add_u32_e32 v162, v111, v101
	v_add_f32_e32 v110, v174, v110
	ds_read_b64_tr_b16 v[162:163], v162
	v_add_u32_e32 v164, v112, v101
	v_add_f32_e32 v110, v175, v110
	ds_read_b64_tr_b16 v[164:165], v164
	v_add_f32_e32 v110, v176, v110
	s_waitcnt lgkmcnt(0)
	v_add_f32_e32 v110, v177, v110
	v_add_f32_e32 v110, v178, v110
	v_add_f32_e32 v110, v179, v110
	v_mfma_f32_16x16x32_bf16 v[106:109], v[150:153], v[146:149], v[106:109]
	v_add_u32_e32 v150, v111, v94
	ds_read_b64_tr_b16 v[150:151], v150
	v_add_u32_e32 v152, v112, v94
	v_mfma_f32_16x16x32_bf16 v[122:125], v[154:157], v[146:149], v[122:125]
	ds_read_b64_tr_b16 v[152:153], v152
	v_add_u32_e32 v154, v111, v95
	ds_read_b64_tr_b16 v[154:155], v154
	v_add_u32_e32 v156, v112, v95
	v_mfma_f32_16x16x32_bf16 v[126:129], v[158:161], v[146:149], v[126:129]
	ds_read_b64_tr_b16 v[156:157], v156
	v_add_u32_e32 v158, v111, v96
	ds_read_b64_tr_b16 v[158:159], v158
	v_add_u32_e32 v160, v112, v96
	ds_read_b64_tr_b16 v[160:161], v160
	v_mfma_f32_16x16x32_bf16 v[130:133], v[162:165], v[146:149], v[130:133]
	v_add_u32_e32 v111, v111, v93
	ds_read_b64_tr_b16 v[162:163], v111
	v_add_u32_e32 v111, v112, v93
	ds_read_b64_tr_b16 v[164:165], v111
	s_waitcnt lgkmcnt(0)
	v_add_f32_e32 v110, v81, v110
	v_add_f32_e32 v110, v88, v110
	v_add_f32_e32 v110, v85, v110
	v_add_f32_e32 v110, v90, v110
	v_add_f32_e32 v110, v87, v110
	v_add_f32_e32 v110, v91, v110
	v_add_f32_e32 v110, v89, v110
	v_add_f32_e32 v110, v92, v110
	ds_bpermute_b32 v80, v80, v110
	v_bfe_u32 v112, v90, 16, 1
	v_add3_u32 v112, v90, v112, s78
	v_mfma_f32_16x16x32_bf16 v[134:137], v[150:153], v[146:149], v[134:137]
	s_waitcnt lgkmcnt(0)
	v_add_f32_e32 v80, v110, v80
	ds_bpermute_b32 v110, v84, v80
	v_mfma_f32_16x16x32_bf16 v[138:141], v[154:157], v[146:149], v[138:141]
	v_bfe_u32 v84, v92, 16, 1
	v_add3_u32 v84, v92, v84, s78
	v_mfma_f32_16x16x32_bf16 v[142:145], v[158:161], v[146:149], v[142:145]
	v_bfe_u32 v92, v85, 16, 1
	v_add3_u32 v85, v85, v92, s78
	v_mfma_f32_16x16x32_bf16 v[102:105], v[162:165], v[146:149], v[102:105]
	v_bfe_u32 v146, v89, 16, 1
	v_add3_u32 v89, v89, v146, s78
	v_cvt_pk_bf16_f32 v88, v81, v88
	v_or3_b32 v81, s46, v83, v120
	v_lshrrev_b32_e32 v89, 16, v89
	v_lshl_add_u32 v81, v81, 8, v86
	v_cvt_pk_bf16_f32 v90, v87, v91
	v_lshrrev_b32_e32 v85, 16, v85
	v_and_or_b32 v91, v84, s79, v89
	v_add3_u32 v83, v86, s54, v97
	v_add_u32_e32 v84, v81, v98
	v_and_or_b32 v89, v112, s79, v85
	ds_read_b64_tr_b16 v[84:85], v84
	v_add_u32_e32 v86, v83, v98
	ds_read_b64_tr_b16 v[86:87], v86
	v_add_u32_e32 v92, v81, v99
	ds_read_b64_tr_b16 v[146:147], v92
	v_add_u32_e32 v92, v83, v99
	ds_read_b64_tr_b16 v[148:149], v92
	v_add_u32_e32 v92, v81, v100
	ds_read_b64_tr_b16 v[150:151], v92
	v_add_u32_e32 v92, v83, v100
	ds_read_b64_tr_b16 v[152:153], v92
	v_add_u32_e32 v92, v81, v101
	ds_read_b64_tr_b16 v[98:99], v92
	v_add_u32_e32 v92, v83, v101
	ds_read_b64_tr_b16 v[100:101], v92
	s_waitcnt lgkmcnt(0)
	v_mfma_f32_16x16x32_bf16 v[84:87], v[84:87], v[88:91], v[106:109]
	v_add_u32_e32 v92, v81, v94
	v_mfma_f32_16x16x32_bf16 v[106:109], v[146:149], v[88:91], v[122:125]
	v_mfma_f32_16x16x32_bf16 v[122:125], v[150:153], v[88:91], v[126:129]
	ds_read_b64_tr_b16 v[126:127], v92
	v_add_u32_e32 v92, v83, v94
	ds_read_b64_tr_b16 v[128:129], v92
	v_mfma_f32_16x16x32_bf16 v[98:101], v[98:101], v[88:91], v[130:133]
	v_add_u32_e32 v92, v81, v95
	ds_read_b64_tr_b16 v[130:131], v92
	v_add_u32_e32 v92, v83, v95
	ds_read_b64_tr_b16 v[132:133], v92
	v_add_u32_e32 v92, v81, v96
	ds_read_b64_tr_b16 v[94:95], v92
	v_add_u32_e32 v92, v83, v96
	ds_read_b64_tr_b16 v[96:97], v92
	v_add_u32_e32 v81, v81, v93
	ds_read_b64_tr_b16 v[146:147], v81
	v_add_u32_e32 v81, v83, v93
	ds_read_b64_tr_b16 v[148:149], v81
	s_waitcnt lgkmcnt(0)
	s_waitcnt lgkmcnt(0)
; #define GAS __attribute__((address_space(1)))
; __device__ __forceinline__ unsigned pk2(float lo, float hi) { return f2bf(lo) | (f2bf(hi) << 16); }
; template <int L>
; __device__ __forceinline__ void layer_body(const Args& args, LAS unsigned char* lds, const int wave, const int G, const int gw, const int NGW, const int lo, const int hi,
;                                            unsigned char* const ws_kernel, const XcdBarrier& bar, int& pid) {
;     ...
;                     const float inv = 1.0f / sum; const int tq = b * SEQ + mq * dil + rho;
;                     GAS bf16* op = (GAS bf16*)(opart + ((size_t)g * (M / 2) + tq) * D + h * HD + 4 * kg);
; #pragma unroll
;                     for (int mt = 0; mt < 8; ++mt) { v2u w; w.x = pk2(acc[mt][0] * inv, acc[mt][1] * inv); w.y = pk2(acc[mt][2] * inv, acc[mt][3] * inv); *(GAS v2u*)(op + 16 * mt) = w; }
;                     if (kg == 0) ((GAS float*)lsebuf)[((size_t)g * (M / 2) + tq) * NH + h] = mx + __log2f(sum);
	v_add_f32_e32 v83, v80, v110
	v_div_scale_f32 v80, s[68:69], v83, v83, 1.0
	v_rcp_f32_e32 v81, v80
	v_div_scale_f32 v110, vcc, 1.0, v83, 1.0
	s_lshl_b32 s3, s12, 7
	v_fma_f32 v92, -v80, v81, 1.0
	v_fmac_f32_e32 v81, v92, v81
	v_mfma_f32_16x16x32_bf16 v[92:95], v[94:97], v[88:91], v[142:145]
	v_mul_f32_e32 v96, v110, v81
	v_fma_f32 v97, -v80, v96, v110
	v_fmac_f32_e32 v96, v97, v81
	v_fma_f32 v80, -v80, v96, v110
	v_div_fmas_f32 v80, v80, v81, v96
	s_and_b32 s3, s3, 0xfffff800
	v_div_fixup_f32 v96, v80, v83, 1.0
	v_lshlrev_b32_e32 v80, s67, v121
	s_or_b32 s2, s2, s3
	v_mfma_f32_16x16x32_bf16 v[126:129], v[126:129], v[88:91], v[134:137]
	v_add_u32_e32 v80, s2, v80
	s_ashr_i32 s67, s66, 31
	s_lshl_b64 s[2:3], s[66:67], 12
	v_mfma_f32_16x16x32_bf16 v[130:133], v[130:133], v[88:91], v[138:141]
	v_ashrrev_i32_e32 v81, 31, v80
	v_lshl_add_u64 v[80:81], s[2:3], 0, v[80:81]
	s_lshl_b32 s12, s4, 8
	v_mfma_f32_16x16x32_bf16 v[88:91], v[146:149], v[88:91], v[102:105]
	v_lshlrev_b32_e32 v112, 1, v120
	v_cmp_eq_u32_e32 vcc, 0, v119
	s_nop 0
	v_mov_b32_e32 v104, v84
	v_mov_b32_e32 v105, v86
	v_pk_mul_f32 v[104:105], v[96:97], v[104:105] op_sel_hi:[0,1]
	v_mov_b32_e32 v86, v85
	v_pk_mul_f32 v[84:85], v[96:97], v[86:87] op_sel_hi:[0,1]
	v_lshlrev_b64 v[102:103], 12, v[80:81]
	v_and_b32_sdwa v97, v85, v118 dst_sel:DWORD dst_unused:UNUSED_PAD src0_sel:WORD_1 src1_sel:DWORD
	v_lshl_add_u64 v[102:103], s[60:61], 0, v[102:103]
	v_and_b32_sdwa v86, v105, v118 dst_sel:DWORD dst_unused:UNUSED_PAD src0_sel:WORD_1 src1_sel:DWORD
	v_add3_u32 v85, v85, v97, s78
	v_lshl_add_u64 v[102:103], v[102:103], 0, s[12:13]
	v_add3_u32 v86, v105, v86, s78
	v_and_b32_e32 v85, 0xffff0000, v85
	v_lshl_add_u64 v[102:103], v[102:103], 0, v[112:113]
	v_or_b32_sdwa v85, v85, v86 dst_sel:DWORD dst_unused:UNUSED_PAD src0_sel:DWORD src1_sel:WORD_1
	v_cvt_pk_bf16_f32 v84, v104, v84
	global_store_dwordx2 v[102:103], v[84:85], off
	v_mov_b32_e32 v84, v106
	v_mov_b32_e32 v85, v108
	v_pk_mul_f32 v[84:85], v[96:97], v[84:85] op_sel_hi:[0,1]
	v_mov_b32_e32 v108, v107
	v_pk_mul_f32 v[86:87], v[96:97], v[108:109] op_sel_hi:[0,1]
	v_and_b32_sdwa v97, v85, v118 dst_sel:DWORD dst_unused:UNUSED_PAD src0_sel:WORD_1 src1_sel:DWORD
	v_add3_u32 v85, v85, v97, s78
	v_and_b32_sdwa v97, v87, v118 dst_sel:DWORD dst_unused:UNUSED_PAD src0_sel:WORD_1 src1_sel:DWORD
	v_add3_u32 v87, v87, v97, s78
	v_and_b32_e32 v87, 0xffff0000, v87
	v_or_b32_sdwa v85, v87, v85 dst_sel:DWORD dst_unused:UNUSED_PAD src0_sel:DWORD src1_sel:WORD_1
	v_cvt_pk_bf16_f32 v84, v84, v86
	global_store_dwordx2 v[102:103], v[84:85], off offset:32
	v_mov_b32_e32 v84, v122
	v_mov_b32_e32 v85, v124
	v_pk_mul_f32 v[84:85], v[96:97], v[84:85] op_sel_hi:[0,1]
	v_mov_b32_e32 v124, v123
	v_pk_mul_f32 v[86:87], v[96:97], v[124:125] op_sel_hi:[0,1]
	v_and_b32_sdwa v97, v85, v118 dst_sel:DWORD dst_unused:UNUSED_PAD src0_sel:WORD_1 src1_sel:DWORD
	v_add3_u32 v85, v85, v97, s78
	v_and_b32_sdwa v97, v87, v118 dst_sel:DWORD dst_unused:UNUSED_PAD src0_sel:WORD_1 src1_sel:DWORD
	v_add3_u32 v87, v87, v97, s78
	v_and_b32_e32 v87, 0xffff0000, v87
	v_or_b32_sdwa v85, v87, v85 dst_sel:DWORD dst_unused:UNUSED_PAD src0_sel:DWORD src1_sel:WORD_1
	v_cvt_pk_bf16_f32 v84, v84, v86
	global_store_dwordx2 v[102:103], v[84:85], off offset:64
	v_mov_b32_e32 v84, v98
	v_mov_b32_e32 v85, v100
	v_pk_mul_f32 v[84:85], v[96:97], v[84:85] op_sel_hi:[0,1]
	v_mov_b32_e32 v100, v99
	v_pk_mul_f32 v[86:87], v[96:97], v[100:101] op_sel_hi:[0,1]
	v_and_b32_sdwa v97, v85, v118 dst_sel:DWORD dst_unused:UNUSED_PAD src0_sel:WORD_1 src1_sel:DWORD
	v_add3_u32 v85, v85, v97, s78
	v_and_b32_sdwa v97, v87, v118 dst_sel:DWORD dst_unused:UNUSED_PAD src0_sel:WORD_1 src1_sel:DWORD
	v_add3_u32 v87, v87, v97, s78
	v_and_b32_e32 v87, 0xffff0000, v87
	v_or_b32_sdwa v85, v87, v85 dst_sel:DWORD dst_unused:UNUSED_PAD src0_sel:DWORD src1_sel:WORD_1
	v_cvt_pk_bf16_f32 v84, v84, v86
	global_store_dwordx2 v[102:103], v[84:85], off offset:96
	v_mov_b32_e32 v84, v126
	v_mov_b32_e32 v85, v128
	v_pk_mul_f32 v[84:85], v[96:97], v[84:85] op_sel_hi:[0,1]
	v_mov_b32_e32 v128, v127
	v_pk_mul_f32 v[86:87], v[96:97], v[128:129] op_sel_hi:[0,1]
	v_and_b32_sdwa v97, v85, v118 dst_sel:DWORD dst_unused:UNUSED_PAD src0_sel:WORD_1 src1_sel:DWORD
	v_add3_u32 v85, v85, v97, s78
	v_and_b32_sdwa v97, v87, v118 dst_sel:DWORD dst_unused:UNUSED_PAD src0_sel:WORD_1 src1_sel:DWORD
	v_add3_u32 v87, v87, v97, s78
	v_and_b32_e32 v87, 0xffff0000, v87
	v_or_b32_sdwa v85, v87, v85 dst_sel:DWORD dst_unused:UNUSED_PAD src0_sel:DWORD src1_sel:WORD_1
	v_cvt_pk_bf16_f32 v84, v84, v86
	global_store_dwordx2 v[102:103], v[84:85], off offset:128
	v_mov_b32_e32 v84, v130
	v_mov_b32_e32 v85, v132
	v_pk_mul_f32 v[84:85], v[96:97], v[84:85] op_sel_hi:[0,1]
	v_mov_b32_e32 v132, v131
	v_pk_mul_f32 v[86:87], v[96:97], v[132:133] op_sel_hi:[0,1]
	v_and_b32_sdwa v97, v85, v118 dst_sel:DWORD dst_unused:UNUSED_PAD src0_sel:WORD_1 src1_sel:DWORD
	v_add3_u32 v85, v85, v97, s78
	v_and_b32_sdwa v97, v87, v118 dst_sel:DWORD dst_unused:UNUSED_PAD src0_sel:WORD_1 src1_sel:DWORD
	v_add3_u32 v87, v87, v97, s78
	v_and_b32_e32 v87, 0xffff0000, v87
	v_or_b32_sdwa v85, v87, v85 dst_sel:DWORD dst_unused:UNUSED_PAD src0_sel:DWORD src1_sel:WORD_1
	v_cvt_pk_bf16_f32 v84, v84, v86
	global_store_dwordx2 v[102:103], v[84:85], off offset:160
	v_mov_b32_e32 v84, v92
	v_mov_b32_e32 v85, v94
	v_pk_mul_f32 v[84:85], v[96:97], v[84:85] op_sel_hi:[0,1]
	v_mov_b32_e32 v94, v93
	v_pk_mul_f32 v[86:87], v[96:97], v[94:95] op_sel_hi:[0,1]
	v_cvt_pk_bf16_f32 v85, v85, v87
	v_cvt_pk_bf16_f32 v84, v84, v86
	global_store_dwordx2 v[102:103], v[84:85], off offset:192
	v_mov_b32_e32 v84, v88
	v_mov_b32_e32 v85, v90
	v_pk_mul_f32 v[84:85], v[96:97], v[84:85] op_sel_hi:[0,1]
	v_mov_b32_e32 v90, v89
	v_pk_mul_f32 v[86:87], v[96:97], v[90:91] op_sel_hi:[0,1]
	v_cvt_pk_bf16_f32 v85, v85, v87
	v_cvt_pk_bf16_f32 v84, v84, v86
	global_store_dwordx2 v[102:103], v[84:85], off offset:224
	s_and_saveexec_b64 s[2:3], vcc
	s_cbranch_execz .LBB0_1685
	v_log_f32_e32 v83, v83
	v_lshlrev_b64 v[80:81], 6, v[80:81]
	v_lshl_add_u64 v[80:81], s[62:63], 0, v[80:81]
	s_lshl_b32 s12, s4, 2
	v_add_f32_e32 v82, v82, v83
	v_lshl_add_u64 v[80:81], v[80:81], 0, s[12:13]
	global_store_dword v[80:81], v82, off
	s_branch .LBB0_1685

; #define LAS __attribute__((address_space(3)))
; __device__ __forceinline__ unsigned pk2(float lo, float hi) { return f2bf(lo) | (f2bf(hi) << 16); }
; template <int L>
; __device__ __forceinline__ void layer_body(const Args& args, LAS unsigned char* lds, const int wave, const int G, const int gw, const int NGW, const int lo, const int hi,
;                                            unsigned char* const ws_kernel, const XcdBarrier& bar, int& pid) {
;     ...
;                     bf16x8 pbf[8];
; #pragma unroll
;                     for (int s = 0; s < 8; ++s) { const f32x4 p0 = sc[2 * s], p1 = sc[2 * s + 1]; v4u w; w.x = pk2(p0[0], p0[1]); w.y = pk2(p0[2], p0[3]); w.z = pk2(p1[0], p1[1]); w.w = pk2(p1[2], p1[3]); pbf[s] = __builtin_bit_cast(bf16x8, w); }
;                     __syncthreads();
; #pragma unroll
;                     for (int i = 0; i < 14; ++i) { const int kid = skey + 32 * i; *(LAS v4u*)(size_t)(IMG + vimg_off(kid, sch)) = rst[i]; }
;                     __syncthreads();
;                     if (unit + GH < UEND) { NA_LOADROWS(unit + GH, rst, D); NA_LOADQ(unit + GH); }
;                     f32x4 acc[8];
; #pragma unroll
;                     for (int mt = 0; mt < 8; ++mt) acc[mt] = (f32x4){0.f, 0.f, 0.f, 0.f};
;                     const int trq = (lane & 15) >> 2, trp = lane & 3;
; #pragma unroll
;                     for (int s = 0; s < 8; ++s) {
;                         const int ir0 = (r0w - krlo + s) * 40 + coloff;
; #pragma unroll
;                         for (int mh = 0; mh < 2; ++mh) {
;                             s16x4 lo[4], hi[4];
; #pragma unroll
;                             for (int m4 = 0; m4 < 4; ++m4) { const int mt = mh * 4 + m4, r0_ = ir0 + 4 * kg + trq, r1_ = ir0 + 16 + 4 * kg + trq, ch_ = 2 * mt + (trp >> 1);
;                                 lo[m4] = tr_read_b64(IMG + vimg_off(r0_, ch_) + 8u * (trp & 1)); hi[m4] = tr_read_b64(IMG + vimg_off(r1_, ch_) + 8u * (trp & 1)); }
;                             asm volatile("s_waitcnt lgkmcnt(0)" ::: "memory"); __builtin_amdgcn_sched_barrier(0);
; #pragma unroll
;                             for (int m4 = 0; m4 < 4; ++m4) { const int mt = mh * 4 + m4; const bf16x8 va = (bf16x8){lo[m4][0], lo[m4][1], lo[m4][2], lo[m4][3], hi[m4][0], hi[m4][1], hi[m4][2], hi[m4][3]};
;                                 acc[mt] = __builtin_amdgcn_mfma_f32_16x16x32_bf16(va, pbf[s], acc[mt], 0, 0, 0); }
.LBB0_3408:
	v_cvt_pk_bf16_f32 v101, v194, v200
	v_cvt_pk_bf16_f32 v100, v190, v198
	v_cvt_pk_bf16_f32 v103, v199, v202
	v_cvt_pk_bf16_f32 v102, v196, v201
	v_cvt_pk_bf16_f32 v97, v186, v193
	v_cvt_pk_bf16_f32 v96, v180, v191
	v_cvt_pk_bf16_f32 v99, v192, v197
	v_cvt_pk_bf16_f32 v98, v188, v195
	v_cvt_pk_bf16_f32 v93, v178, v185
	v_cvt_pk_bf16_f32 v92, v177, v182
	v_cvt_pk_bf16_f32 v95, v184, v189
	v_cvt_pk_bf16_f32 v94, v179, v187
	v_cvt_pk_bf16_f32 v89, v142, v148
	v_cvt_pk_bf16_f32 v88, v138, v146
	v_cvt_pk_bf16_f32 v91, v147, v152
	v_cvt_pk_bf16_f32 v90, v144, v150
	v_cvt_pk_bf16_f32 v85, v134, v141
	v_cvt_pk_bf16_f32 v84, v130, v139
	v_cvt_pk_bf16_f32 v87, v140, v145
	v_cvt_pk_bf16_f32 v86, v136, v143
	v_cvt_pk_bf16_f32 v81, v126, v133
	v_cvt_pk_bf16_f32 v80, v122, v131
	v_cvt_pk_bf16_f32 v83, v132, v137
	v_cvt_pk_bf16_f32 v82, v128, v135
	v_cvt_pk_bf16_f32 v79, v124, v129
	v_cvt_pk_bf16_f32 v76, v75, v123
	v_cvt_pk_bf16_f32 v78, v120, v127
	v_cvt_pk_bf16_f32 v77, v118, v125
	v_bfe_u32 v114, v115, 16, 1
	v_add3_u32 v114, v115, v114, s64
	v_bfe_u32 v115, v72, 16, 1
	v_add3_u32 v72, v72, v115, s64
	v_lshrrev_b32_e32 v112, 2, v112
	v_lshrrev_b32_e32 v72, 16, v72
	v_cvt_pk_bf16_f32 v75, v116, v121
	v_or_b32_e32 v115, v109, v112
	s_add_i32 s68, s68, s67
	v_cvt_pk_bf16_f32 v73, v73, v117
	v_and_or_b32 v72, v114, s65, v72
	v_or_b32_e32 v113, 16, v115
	v_bfe_u32 v112, v111, 1, 1
	v_lshlrev_b32_e32 v111, 3, v111
	v_add_u32_e32 v114, s68, v115
	v_and_or_b32 v111, v111, 8, 0
	v_add_u32_e32 v116, s68, v113
	v_lshlrev_b32_e32 v117, 2, v114
	v_and_b32_e32 v152, 12, v117
	v_bfe_u32 v153, v114, 2, 2
	v_lshl_add_u32 v154, v114, 8, v111
	v_lshlrev_b32_e32 v114, 2, v116
	v_and_b32_e32 v155, 12, v114
	v_bitop3_b32 v114, v152, v112, v153 bitop3:0x36
	v_bfe_u32 v156, v116, 2, 2
	v_lshl_add_u32 v253, v114, 4, v154
	v_lshl_add_u32 v157, v116, 8, v111
	ds_read_b64_tr_b16 v[120:121], v253
	v_bitop3_b32 v114, v155, v112, v156 bitop3:0x36
	v_lshl_add_u32 v252, v114, 4, v157
	ds_read_b64_tr_b16 v[122:123], v252
	v_or_b32_e32 v114, 2, v112
	v_xor_b32_e32 v116, 0x20, v253
	ds_read_b64_tr_b16 v[124:125], v116
	v_xor_b32_e32 v116, 0x20, v252
	ds_read_b64_tr_b16 v[126:127], v116
	v_or_b32_e32 v116, 4, v112
	v_xor_b32_e32 v117, 0x40, v253
	ds_read_b64_tr_b16 v[128:129], v117
	v_xor_b32_e32 v117, 0x40, v252
	ds_read_b64_tr_b16 v[130:131], v117
	v_xor_b32_e32 v118, 0x60, v253
	ds_read_b64_tr_b16 v[132:133], v118
	v_xor_b32_e32 v118, 0x60, v252
	ds_read_b64_tr_b16 v[134:135], v118
	s_waitcnt lgkmcnt(0)
	v_cvt_pk_bf16_f32 v74, v74, v119
	v_add_f32_e32 v104, v149, v151
	v_xor_b32_e32 v119, 0x80, v253
	v_mfma_f32_16x16x32_bf16 v[136:139], v[120:123], v[100:103], 0
	ds_read_b64_tr_b16 v[122:123], v119
	v_xor_b32_e32 v119, 0x80, v252
	v_mfma_f32_16x16x32_bf16 v[140:143], v[124:127], v[100:103], 0
	ds_read_b64_tr_b16 v[124:125], v119
	v_xor_b32_e32 v120, 0xa0, v253
	v_mfma_f32_16x16x32_bf16 v[126:129], v[128:131], v[100:103], 0
	ds_read_b64_tr_b16 v[130:131], v120
	v_xor_b32_e32 v120, 0xa0, v252
	v_mfma_f32_16x16x32_bf16 v[144:147], v[132:135], v[100:103], 0
	ds_read_b64_tr_b16 v[132:133], v120
	v_xor_b32_e32 v121, 0xc0, v253
	ds_read_b64_tr_b16 v[148:149], v121
	v_xor_b32_e32 v121, 0xc0, v252
	ds_read_b64_tr_b16 v[150:151], v121
	v_or_b32_e32 v121, 14, v112
	v_xor_b32_e32 v134, 0xe0, v253
	ds_read_b64_tr_b16 v[152:153], v134
	v_xor_b32_e32 v134, 0xe0, v252
	ds_read_b64_tr_b16 v[154:155], v134
	s_waitcnt lgkmcnt(0)
	s_add_i32 s69, s69, s67
	v_add_u32_e32 v134, s69, v115
	v_add_u32_e32 v135, s69, v113
	v_lshlrev_b32_e32 v156, 2, v134
	v_and_b32_e32 v168, 12, v156
	v_bfe_u32 v169, v134, 2, 2
	v_lshl_add_u32 v170, v134, 8, v111
	v_lshlrev_b32_e32 v134, 2, v135
	v_and_b32_e32 v171, 12, v134
	v_bitop3_b32 v134, v168, v112, v169 bitop3:0x36
	v_bfe_u32 v172, v135, 2, 2
	v_lshl_add_u32 v253, v134, 4, v170
	v_mfma_f32_16x16x32_bf16 v[122:125], v[122:125], v[100:103], 0
	v_lshl_add_u32 v173, v135, 8, v111
	v_mfma_f32_16x16x32_bf16 v[130:133], v[130:133], v[100:103], 0
	v_mfma_f32_16x16x32_bf16 v[148:151], v[148:151], v[100:103], 0
	v_mfma_f32_16x16x32_bf16 v[100:103], v[152:155], v[100:103], 0
	ds_read_b64_tr_b16 v[152:153], v253
	v_bitop3_b32 v134, v171, v112, v172 bitop3:0x36
	v_lshl_add_u32 v252, v134, 4, v173
	ds_read_b64_tr_b16 v[154:155], v252
	v_xor_b32_e32 v134, 0x20, v253
	ds_read_b64_tr_b16 v[156:157], v134
	v_xor_b32_e32 v134, 0x20, v252
	ds_read_b64_tr_b16 v[158:159], v134
	v_xor_b32_e32 v134, 0x40, v253
	ds_read_b64_tr_b16 v[160:161], v134
	v_xor_b32_e32 v134, 0x40, v252
	ds_read_b64_tr_b16 v[162:163], v134
	v_xor_b32_e32 v134, 0x60, v253
	ds_read_b64_tr_b16 v[164:165], v134
	v_xor_b32_e32 v134, 0x60, v252
	ds_read_b64_tr_b16 v[166:167], v134
	s_waitcnt lgkmcnt(0)
	v_xor_b32_e32 v174, 0x80, v253
	v_mfma_f32_16x16x32_bf16 v[134:137], v[152:155], v[96:99], v[136:139]
	ds_read_b64_tr_b16 v[138:139], v174
	v_xor_b32_e32 v174, 0x80, v252
	v_mfma_f32_16x16x32_bf16 v[152:155], v[156:159], v[96:99], v[140:143]
	ds_read_b64_tr_b16 v[140:141], v174
	v_mfma_f32_16x16x32_bf16 v[126:129], v[160:163], v[96:99], v[126:129]
	s_nop 0
	v_xor_b32_e32 v142, 0xa0, v253
	ds_read_b64_tr_b16 v[142:143], v142
	v_xor_b32_e32 v160, 0xa0, v252
	v_mfma_f32_16x16x32_bf16 v[156:159], v[164:167], v[96:99], v[144:147]
	ds_read_b64_tr_b16 v[144:145], v160
	s_nop 2
	v_xor_b32_e32 v146, 0xc0, v253
	ds_read_b64_tr_b16 v[160:161], v146
	v_xor_b32_e32 v146, 0xc0, v252
	ds_read_b64_tr_b16 v[162:163], v146
	v_xor_b32_e32 v146, 0xe0, v253
	ds_read_b64_tr_b16 v[164:165], v146
	v_xor_b32_e32 v146, 0xe0, v252
	ds_read_b64_tr_b16 v[166:167], v146
	s_waitcnt lgkmcnt(0)
; __device__ __forceinline__ s16x4 tr_read_b64(unsigned addr) { s16x4 r; asm volatile("ds_read_b64_tr_b16 %0, %1" : "=v"(r) : "v"(addr) : "memory"); return r; }
; template <int L>
; __device__ __forceinline__ void layer_body(const Args& args, LAS unsigned char* lds, const int wave, const int G, const int gw, const int NGW, const int lo, const int hi,
;                                            unsigned char* const ws_kernel, const XcdBarrier& bar, int& pid) {
;     ...
;                     const int trq = (lane & 15) >> 2, trp = lane & 3;
; #pragma unroll
;                     for (int s = 0; s < 8; ++s) {
;                         const int ir0 = (r0w - krlo + s) * 40 + coloff;
; #pragma unroll
;                         for (int mh = 0; mh < 2; ++mh) {
;                             s16x4 lo[4], hi[4];
; #pragma unroll
;                             for (int m4 = 0; m4 < 4; ++m4) { const int mt = mh * 4 + m4, r0_ = ir0 + 4 * kg + trq, r1_ = ir0 + 16 + 4 * kg + trq, ch_ = 2 * mt + (trp >> 1);
;                                 lo[m4] = tr_read_b64(IMG + vimg_off(r0_, ch_) + 8u * (trp & 1)); hi[m4] = tr_read_b64(IMG + vimg_off(r1_, ch_) + 8u * (trp & 1)); }
;                             asm volatile("s_waitcnt lgkmcnt(0)" ::: "memory"); __builtin_amdgcn_sched_barrier(0);
; #pragma unroll
;                             for (int m4 = 0; m4 < 4; ++m4) { const int mt = mh * 4 + m4; const bf16x8 va = (bf16x8){lo[m4][0], lo[m4][1], lo[m4][2], lo[m4][3], hi[m4][0], hi[m4][1], hi[m4][2], hi[m4][3]};
;                                 acc[mt] = __builtin_amdgcn_mfma_f32_16x16x32_bf16(va, pbf[s], acc[mt], 0, 0, 0); }
	s_add_i32 s70, s70, s67
	v_add_u32_e32 v146, s70, v115
	v_mfma_f32_16x16x32_bf16 v[122:125], v[138:141], v[96:99], v[122:125]
	v_add_u32_e32 v147, s70, v113
	v_lshlrev_b32_e32 v138, 2, v146
	v_and_b32_e32 v168, 12, v138
	v_mfma_f32_16x16x32_bf16 v[130:133], v[142:145], v[96:99], v[130:133]
	v_bfe_u32 v169, v146, 2, 2
	v_lshlrev_b32_e32 v142, 2, v147
	v_lshl_add_u32 v170, v146, 8, v111
	v_mfma_f32_16x16x32_bf16 v[138:141], v[160:163], v[96:99], v[148:151]
	v_and_b32_e32 v171, 12, v142
	v_bfe_u32 v172, v147, 2, 2
	v_lshl_add_u32 v173, v147, 8, v111
	v_mfma_f32_16x16x32_bf16 v[96:99], v[164:167], v[96:99], v[100:103]
	v_bitop3_b32 v142, v168, v114, v169 bitop3:0x36
	v_lshl_add_u32 v142, v142, 4, v170
	v_bitop3_b32 v144, v171, v114, v172 bitop3:0x36
	v_bitop3_b32 v100, v168, v112, v169 bitop3:0x36
	v_lshl_add_u32 v253, v100, 4, v170
	v_bitop3_b32 v102, v171, v112, v172 bitop3:0x36
	ds_read_b64_tr_b16 v[100:101], v253
	v_lshl_add_u32 v252, v102, 4, v173
	ds_read_b64_tr_b16 v[102:103], v252
	ds_read_b64_tr_b16 v[142:143], v142
	v_lshl_add_u32 v144, v144, 4, v173
	ds_read_b64_tr_b16 v[144:145], v144
	v_xor_b32_e32 v146, 0x40, v253
	ds_read_b64_tr_b16 v[146:147], v146
	v_xor_b32_e32 v148, 0x40, v252
	ds_read_b64_tr_b16 v[148:149], v148
	v_xor_b32_e32 v150, 0x60, v253
	ds_read_b64_tr_b16 v[160:161], v150
	v_xor_b32_e32 v150, 0x60, v252
	ds_read_b64_tr_b16 v[162:163], v150
	s_waitcnt lgkmcnt(0)
	v_mfma_f32_16x16x32_bf16 v[100:103], v[100:103], v[92:95], v[134:137]
	v_xor_b32_e32 v150, 0x80, v253
	ds_read_b64_tr_b16 v[134:135], v150
	v_mfma_f32_16x16x32_bf16 v[126:129], v[146:149], v[92:95], v[126:129]
	v_xor_b32_e32 v136, 0x80, v252
	ds_read_b64_tr_b16 v[136:137], v136
	v_mfma_f32_16x16x32_bf16 v[142:145], v[142:145], v[92:95], v[152:155]
	v_xor_b32_e32 v150, 0xa0, v253
	ds_read_b64_tr_b16 v[146:147], v150
	v_xor_b32_e32 v148, 0xa0, v252
	v_mfma_f32_16x16x32_bf16 v[150:153], v[160:163], v[92:95], v[156:159]
	ds_read_b64_tr_b16 v[148:149], v148
	v_xor_b32_e32 v154, 0xc0, v253
	ds_read_b64_tr_b16 v[154:155], v154
	v_xor_b32_e32 v156, 0xc0, v252
	ds_read_b64_tr_b16 v[156:157], v156
	v_xor_b32_e32 v158, 0xe0, v253
	ds_read_b64_tr_b16 v[158:159], v158
	v_xor_b32_e32 v160, 0xe0, v252
	ds_read_b64_tr_b16 v[160:161], v160
	s_waitcnt lgkmcnt(0)
	s_add_i32 s71, s71, s67
	v_add_u32_e32 v162, s71, v115
	v_mfma_f32_16x16x32_bf16 v[122:125], v[134:137], v[92:95], v[122:125]
	v_add_u32_e32 v163, s71, v113
	v_lshlrev_b32_e32 v134, 2, v162
	v_and_b32_e32 v164, 12, v134
	v_mfma_f32_16x16x32_bf16 v[130:133], v[146:149], v[92:95], v[130:133]
	v_bfe_u32 v165, v162, 2, 2
	v_lshlrev_b32_e32 v146, 2, v163
	v_lshl_add_u32 v162, v162, 8, v111
	v_mfma_f32_16x16x32_bf16 v[134:137], v[154:157], v[92:95], v[138:141]
	v_and_b32_e32 v166, 12, v146
	v_bfe_u32 v167, v163, 2, 2
	v_lshl_add_u32 v163, v163, 8, v111
	v_mfma_f32_16x16x32_bf16 v[92:95], v[158:161], v[92:95], v[96:99]
	v_bitop3_b32 v138, v164, v114, v165 bitop3:0x36
	v_lshl_add_u32 v138, v138, 4, v162
	v_bitop3_b32 v140, v166, v114, v167 bitop3:0x36
	v_bitop3_b32 v96, v164, v112, v165 bitop3:0x36
	v_lshl_add_u32 v253, v96, 4, v162
	v_bitop3_b32 v98, v166, v112, v167 bitop3:0x36
	ds_read_b64_tr_b16 v[96:97], v253
	v_lshl_add_u32 v252, v98, 4, v163
	ds_read_b64_tr_b16 v[98:99], v252
	ds_read_b64_tr_b16 v[138:139], v138
	v_lshl_add_u32 v140, v140, 4, v163
	ds_read_b64_tr_b16 v[140:141], v140
	v_xor_b32_e32 v146, 0x40, v253
	ds_read_b64_tr_b16 v[146:147], v146
	v_xor_b32_e32 v148, 0x40, v252
	ds_read_b64_tr_b16 v[148:149], v148
	v_xor_b32_e32 v154, 0x60, v253
	ds_read_b64_tr_b16 v[154:155], v154
	v_xor_b32_e32 v156, 0x60, v252
	ds_read_b64_tr_b16 v[156:157], v156
	s_waitcnt lgkmcnt(0)
	v_mfma_f32_16x16x32_bf16 v[96:99], v[96:99], v[88:91], v[100:103]
	v_xor_b32_e32 v158, 0x80, v253
	ds_read_b64_tr_b16 v[100:101], v158
	v_mfma_f32_16x16x32_bf16 v[138:141], v[138:141], v[88:91], v[142:145]
	s_nop 0
	v_xor_b32_e32 v102, 0x80, v252
	ds_read_b64_tr_b16 v[102:103], v102
	v_mfma_f32_16x16x32_bf16 v[126:129], v[146:149], v[88:91], v[126:129]
	v_xor_b32_e32 v142, 0xa0, v253
	ds_read_b64_tr_b16 v[142:143], v142
	v_xor_b32_e32 v144, 0xa0, v252
	v_mfma_f32_16x16x32_bf16 v[146:149], v[154:157], v[88:91], v[150:153]
	ds_read_b64_tr_b16 v[144:145], v144
	v_xor_b32_e32 v154, 0xe0, v253
	v_xor_b32_e32 v150, 0xc0, v253
	ds_read_b64_tr_b16 v[150:151], v150
	v_xor_b32_e32 v152, 0xc0, v252
	ds_read_b64_tr_b16 v[152:153], v152
	ds_read_b64_tr_b16 v[154:155], v154
	v_xor_b32_e32 v156, 0xe0, v252
	ds_read_b64_tr_b16 v[156:157], v156
	s_waitcnt lgkmcnt(0)
	s_add_i32 s72, s72, s67
	v_add_u32_e32 v158, s72, v115
	v_mfma_f32_16x16x32_bf16 v[100:103], v[100:103], v[88:91], v[122:125]
	v_add_u32_e32 v159, s72, v113
	v_bfe_u32 v161, v158, 2, 2
	v_bfe_u32 v163, v159, 2, 2
	v_lshlrev_b32_e32 v122, 2, v158
	v_and_b32_e32 v160, 12, v122
	v_mfma_f32_16x16x32_bf16 v[122:125], v[142:145], v[88:91], v[130:133]
	v_lshlrev_b32_e32 v142, 2, v159
	v_lshl_add_u32 v158, v158, 8, v111
	v_and_b32_e32 v162, 12, v142
	v_mfma_f32_16x16x32_bf16 v[130:133], v[150:153], v[88:91], v[134:137]
	v_lshl_add_u32 v159, v159, 8, v111
	v_bitop3_b32 v142, v160, v116, v161 bitop3:0x36
	v_lshl_add_u32 v142, v142, 4, v158
	v_mfma_f32_16x16x32_bf16 v[88:91], v[154:157], v[88:91], v[92:95]
	v_bitop3_b32 v134, v160, v114, v161 bitop3:0x36
	v_lshl_add_u32 v134, v134, 4, v158
	v_bitop3_b32 v136, v162, v114, v163 bitop3:0x36
	v_bitop3_b32 v92, v160, v112, v161 bitop3:0x36
	v_lshl_add_u32 v253, v92, 4, v158
	v_bitop3_b32 v94, v162, v112, v163 bitop3:0x36
	ds_read_b64_tr_b16 v[92:93], v253
	v_lshl_add_u32 v252, v94, 4, v159
	ds_read_b64_tr_b16 v[94:95], v252
	ds_read_b64_tr_b16 v[134:135], v134
	v_lshl_add_u32 v136, v136, 4, v159
	ds_read_b64_tr_b16 v[136:137], v136
	ds_read_b64_tr_b16 v[142:143], v142
	v_xor_b32_e32 v144, 0x40, v252
	ds_read_b64_tr_b16 v[144:145], v144
	v_xor_b32_e32 v150, 0x60, v253
	ds_read_b64_tr_b16 v[150:151], v150
	v_xor_b32_e32 v152, 0x60, v252
	ds_read_b64_tr_b16 v[152:153], v152
	s_waitcnt lgkmcnt(0)
; __device__ __forceinline__ s16x4 tr_read_b64(unsigned addr) { s16x4 r; asm volatile("ds_read_b64_tr_b16 %0, %1" : "=v"(r) : "v"(addr) : "memory"); return r; }
; template <int L>
; __device__ __forceinline__ void layer_body(const Args& args, LAS unsigned char* lds, const int wave, const int G, const int gw, const int NGW, const int lo, const int hi,
;                                            unsigned char* const ws_kernel, const XcdBarrier& bar, int& pid) {
;     ...
;                     const int trq = (lane & 15) >> 2, trp = lane & 3;
; #pragma unroll
;                     for (int s = 0; s < 8; ++s) {
;                         const int ir0 = (r0w - krlo + s) * 40 + coloff;
; #pragma unroll
;                         for (int mh = 0; mh < 2; ++mh) {
;                             s16x4 lo[4], hi[4];
; #pragma unroll
;                             for (int m4 = 0; m4 < 4; ++m4) { const int mt = mh * 4 + m4, r0_ = ir0 + 4 * kg + trq, r1_ = ir0 + 16 + 4 * kg + trq, ch_ = 2 * mt + (trp >> 1);
;                                 lo[m4] = tr_read_b64(IMG + vimg_off(r0_, ch_) + 8u * (trp & 1)); hi[m4] = tr_read_b64(IMG + vimg_off(r1_, ch_) + 8u * (trp & 1)); }
;                             asm volatile("s_waitcnt lgkmcnt(0)" ::: "memory"); __builtin_amdgcn_sched_barrier(0);
; #pragma unroll
;                             for (int m4 = 0; m4 < 4; ++m4) { const int mt = mh * 4 + m4; const bf16x8 va = (bf16x8){lo[m4][0], lo[m4][1], lo[m4][2], lo[m4][3], hi[m4][0], hi[m4][1], hi[m4][2], hi[m4][3]};
;                                 acc[mt] = __builtin_amdgcn_mfma_f32_16x16x32_bf16(va, pbf[s], acc[mt], 0, 0, 0); }
	v_mfma_f32_16x16x32_bf16 v[92:95], v[92:95], v[84:87], v[96:99]
	v_xor_b32_e32 v154, 0x80, v253
	ds_read_b64_tr_b16 v[96:97], v154
	v_mfma_f32_16x16x32_bf16 v[134:137], v[134:137], v[84:87], v[138:141]
	s_nop 0
	v_xor_b32_e32 v98, 0x80, v252
	ds_read_b64_tr_b16 v[98:99], v98
	v_mfma_f32_16x16x32_bf16 v[126:129], v[142:145], v[84:87], v[126:129]
	v_xor_b32_e32 v138, 0xa0, v253
	ds_read_b64_tr_b16 v[138:139], v138
	v_xor_b32_e32 v140, 0xa0, v252
	v_mfma_f32_16x16x32_bf16 v[142:145], v[150:153], v[84:87], v[146:149]
	ds_read_b64_tr_b16 v[140:141], v140
	v_xor_b32_e32 v150, 0xe0, v253
	v_xor_b32_e32 v146, 0xc0, v253
	ds_read_b64_tr_b16 v[146:147], v146
	v_xor_b32_e32 v148, 0xc0, v252
	ds_read_b64_tr_b16 v[148:149], v148
	ds_read_b64_tr_b16 v[150:151], v150
	v_xor_b32_e32 v152, 0xe0, v252
	ds_read_b64_tr_b16 v[152:153], v152
	s_waitcnt lgkmcnt(0)
	s_add_i32 s74, s74, s67
	v_add_u32_e32 v154, s74, v115
	v_mfma_f32_16x16x32_bf16 v[96:99], v[96:99], v[84:87], v[100:103]
	v_add_u32_e32 v155, s74, v113
	v_bfe_u32 v157, v154, 2, 2
	v_bfe_u32 v159, v155, 2, 2
	v_lshlrev_b32_e32 v100, 2, v154
	v_and_b32_e32 v156, 12, v100
	v_mfma_f32_16x16x32_bf16 v[100:103], v[138:141], v[84:87], v[122:125]
	v_lshlrev_b32_e32 v138, 2, v155
	v_lshl_add_u32 v154, v154, 8, v111
	v_and_b32_e32 v158, 12, v138
	v_mfma_f32_16x16x32_bf16 v[122:125], v[146:149], v[84:87], v[130:133]
	v_lshl_add_u32 v155, v155, 8, v111
	v_bitop3_b32 v138, v156, v116, v157 bitop3:0x36
	v_lshl_add_u32 v138, v138, 4, v154
	v_mfma_f32_16x16x32_bf16 v[84:87], v[150:153], v[84:87], v[88:91]
	v_bitop3_b32 v130, v156, v114, v157 bitop3:0x36
	v_lshl_add_u32 v130, v130, 4, v154
	v_bitop3_b32 v132, v158, v114, v159 bitop3:0x36
	v_bitop3_b32 v88, v156, v112, v157 bitop3:0x36
	v_lshl_add_u32 v253, v88, 4, v154
	v_bitop3_b32 v90, v158, v112, v159 bitop3:0x36
	ds_read_b64_tr_b16 v[88:89], v253
	v_lshl_add_u32 v252, v90, 4, v155
	ds_read_b64_tr_b16 v[90:91], v252
	ds_read_b64_tr_b16 v[130:131], v130
	v_lshl_add_u32 v132, v132, 4, v155
	ds_read_b64_tr_b16 v[132:133], v132
	ds_read_b64_tr_b16 v[138:139], v138
	v_xor_b32_e32 v140, 0x40, v252
	ds_read_b64_tr_b16 v[140:141], v140
	v_xor_b32_e32 v146, 0x60, v253
	ds_read_b64_tr_b16 v[146:147], v146
	v_xor_b32_e32 v148, 0x60, v252
	ds_read_b64_tr_b16 v[148:149], v148
	s_waitcnt lgkmcnt(0)
	v_mfma_f32_16x16x32_bf16 v[88:91], v[88:91], v[80:83], v[92:95]
	v_xor_b32_e32 v150, 0x80, v253
	ds_read_b64_tr_b16 v[92:93], v150
	v_mfma_f32_16x16x32_bf16 v[130:133], v[130:133], v[80:83], v[134:137]
	s_nop 0
	v_xor_b32_e32 v94, 0x80, v252
	ds_read_b64_tr_b16 v[94:95], v94
	v_mfma_f32_16x16x32_bf16 v[126:129], v[138:141], v[80:83], v[126:129]
	v_xor_b32_e32 v134, 0xa0, v253
	ds_read_b64_tr_b16 v[134:135], v134
	v_xor_b32_e32 v136, 0xa0, v252
	v_mfma_f32_16x16x32_bf16 v[138:141], v[146:149], v[80:83], v[142:145]
	ds_read_b64_tr_b16 v[136:137], v136
	v_xor_b32_e32 v146, 0xe0, v253
	v_xor_b32_e32 v142, 0xc0, v253
	ds_read_b64_tr_b16 v[142:143], v142
	v_xor_b32_e32 v144, 0xc0, v252
	ds_read_b64_tr_b16 v[144:145], v144
	ds_read_b64_tr_b16 v[146:147], v146
	v_xor_b32_e32 v148, 0xe0, v252
	ds_read_b64_tr_b16 v[148:149], v148
	s_waitcnt lgkmcnt(0)
	s_add_i32 s75, s75, s67
	v_add_u32_e32 v150, s75, v115
	v_mfma_f32_16x16x32_bf16 v[92:95], v[92:95], v[80:83], v[96:99]
	v_add_u32_e32 v151, s75, v113
	v_bfe_u32 v153, v150, 2, 2
	v_bfe_u32 v155, v151, 2, 2
	v_lshlrev_b32_e32 v96, 2, v150
	v_and_b32_e32 v152, 12, v96
	v_mfma_f32_16x16x32_bf16 v[96:99], v[134:137], v[80:83], v[100:103]
	v_lshlrev_b32_e32 v134, 2, v151
	v_lshl_add_u32 v150, v150, 8, v111
	v_and_b32_e32 v154, 12, v134
	v_mfma_f32_16x16x32_bf16 v[100:103], v[142:145], v[80:83], v[122:125]
	v_lshl_add_u32 v151, v151, 8, v111
	v_bitop3_b32 v134, v152, v116, v153 bitop3:0x36
	v_lshl_add_u32 v134, v134, 4, v150
	v_mfma_f32_16x16x32_bf16 v[80:83], v[146:149], v[80:83], v[84:87]
	v_bitop3_b32 v122, v152, v114, v153 bitop3:0x36
	v_lshl_add_u32 v122, v122, 4, v150
	v_bitop3_b32 v124, v154, v114, v155 bitop3:0x36
	v_bitop3_b32 v84, v152, v112, v153 bitop3:0x36
	v_lshl_add_u32 v253, v84, 4, v150
	v_bitop3_b32 v86, v154, v112, v155 bitop3:0x36
	ds_read_b64_tr_b16 v[84:85], v253
	v_lshl_add_u32 v252, v86, 4, v151
	ds_read_b64_tr_b16 v[86:87], v252
	ds_read_b64_tr_b16 v[122:123], v122
	v_lshl_add_u32 v124, v124, 4, v151
	ds_read_b64_tr_b16 v[124:125], v124
	ds_read_b64_tr_b16 v[134:135], v134
	v_xor_b32_e32 v136, 0x40, v252
	ds_read_b64_tr_b16 v[136:137], v136
	v_xor_b32_e32 v142, 0x60, v253
	ds_read_b64_tr_b16 v[142:143], v142
	v_xor_b32_e32 v144, 0x60, v252
	ds_read_b64_tr_b16 v[144:145], v144
	s_waitcnt lgkmcnt(0)
	v_mfma_f32_16x16x32_bf16 v[84:87], v[84:87], v[76:79], v[88:91]
	v_xor_b32_e32 v146, 0x80, v253
	ds_read_b64_tr_b16 v[88:89], v146
	v_mfma_f32_16x16x32_bf16 v[122:125], v[122:125], v[76:79], v[130:133]
	s_nop 0
	v_xor_b32_e32 v90, 0x80, v252
	ds_read_b64_tr_b16 v[90:91], v90
	v_mfma_f32_16x16x32_bf16 v[126:129], v[134:137], v[76:79], v[126:129]
	v_xor_b32_e32 v130, 0xa0, v253
	ds_read_b64_tr_b16 v[130:131], v130
	v_xor_b32_e32 v132, 0xa0, v252
	v_mfma_f32_16x16x32_bf16 v[134:137], v[142:145], v[76:79], v[138:141]
	ds_read_b64_tr_b16 v[132:133], v132
	v_xor_b32_e32 v142, 0xe0, v253
	v_xor_b32_e32 v138, 0xc0, v253
	ds_read_b64_tr_b16 v[138:139], v138
	v_xor_b32_e32 v140, 0xc0, v252
	ds_read_b64_tr_b16 v[140:141], v140
	ds_read_b64_tr_b16 v[142:143], v142
	v_xor_b32_e32 v144, 0xe0, v252
	ds_read_b64_tr_b16 v[144:145], v144
	s_waitcnt lgkmcnt(0)
; __device__ __forceinline__ s16x4 tr_read_b64(unsigned addr) { s16x4 r; asm volatile("ds_read_b64_tr_b16 %0, %1" : "=v"(r) : "v"(addr) : "memory"); return r; }
; template <int L>
; __device__ __forceinline__ void layer_body(const Args& args, LAS unsigned char* lds, const int wave, const int G, const int gw, const int NGW, const int lo, const int hi,
;                                            unsigned char* const ws_kernel, const XcdBarrier& bar, int& pid) {
;     ...
;                     const int trq = (lane & 15) >> 2, trp = lane & 3;
; #pragma unroll
;                     for (int s = 0; s < 8; ++s) {
;                         const int ir0 = (r0w - krlo + s) * 40 + coloff;
; #pragma unroll
;                         for (int mh = 0; mh < 2; ++mh) {
;                             s16x4 lo[4], hi[4];
; #pragma unroll
;                             for (int m4 = 0; m4 < 4; ++m4) { const int mt = mh * 4 + m4, r0_ = ir0 + 4 * kg + trq, r1_ = ir0 + 16 + 4 * kg + trq, ch_ = 2 * mt + (trp >> 1);
;                                 lo[m4] = tr_read_b64(IMG + vimg_off(r0_, ch_) + 8u * (trp & 1)); hi[m4] = tr_read_b64(IMG + vimg_off(r1_, ch_) + 8u * (trp & 1)); }
;                             asm volatile("s_waitcnt lgkmcnt(0)" ::: "memory"); __builtin_amdgcn_sched_barrier(0);
; #pragma unroll
;                             for (int m4 = 0; m4 < 4; ++m4) { const int mt = mh * 4 + m4; const bf16x8 va = (bf16x8){lo[m4][0], lo[m4][1], lo[m4][2], lo[m4][3], hi[m4][0], hi[m4][1], hi[m4][2], hi[m4][3]};
;                                 acc[mt] = __builtin_amdgcn_mfma_f32_16x16x32_bf16(va, pbf[s], acc[mt], 0, 0, 0); }
	s_add_i32 s76, s76, s67
	v_add_u32_e32 v115, s76, v115
	v_mfma_f32_16x16x32_bf16 v[88:91], v[88:91], v[76:79], v[92:95]
	v_add_u32_e32 v113, s76, v113
	v_bfe_u32 v147, v115, 2, 2
	v_lshl_add_u32 v148, v115, 8, v111
	v_lshlrev_b32_e32 v92, 2, v115
	v_and_b32_e32 v146, 12, v92
	v_lshlrev_b32_e32 v115, 2, v113
	v_mfma_f32_16x16x32_bf16 v[92:95], v[130:133], v[76:79], v[96:99]
	v_lshl_add_u32 v111, v113, 8, v111
	v_mfma_f32_16x16x32_bf16 v[96:99], v[138:141], v[76:79], v[100:103]
	v_and_b32_e32 v138, 12, v115
	v_bfe_u32 v139, v113, 2, 2
	v_mfma_f32_16x16x32_bf16 v[76:79], v[142:145], v[76:79], v[80:83]
	v_bitop3_b32 v100, v146, v114, v147 bitop3:0x36
	v_lshl_add_u32 v100, v100, 4, v148
	v_bitop3_b32 v102, v138, v114, v139 bitop3:0x36
	v_bitop3_b32 v80, v146, v112, v147 bitop3:0x36
	v_lshl_add_u32 v253, v80, 4, v148
	v_bitop3_b32 v82, v138, v112, v139 bitop3:0x36
	ds_read_b64_tr_b16 v[80:81], v253
	v_lshl_add_u32 v252, v82, 4, v111
	ds_read_b64_tr_b16 v[82:83], v252
	ds_read_b64_tr_b16 v[100:101], v100
	v_lshl_add_u32 v102, v102, 4, v111
	ds_read_b64_tr_b16 v[102:103], v102
	v_xor_b32_e32 v112, 0x40, v253
	ds_read_b64_tr_b16 v[112:113], v112
	v_xor_b32_e32 v114, 0x40, v252
	ds_read_b64_tr_b16 v[114:115], v114
	v_xor_b32_e32 v116, 0x60, v253
	ds_read_b64_tr_b16 v[130:131], v116
	v_xor_b32_e32 v116, 0x60, v252
	ds_read_b64_tr_b16 v[132:133], v116
	s_waitcnt lgkmcnt(0)
	v_xor_b32_e32 v116, 0x80, v253
	v_mfma_f32_16x16x32_bf16 v[80:83], v[80:83], v[72:75], v[84:87]
	ds_read_b64_tr_b16 v[84:85], v116
	v_xor_b32_e32 v116, 0xa0, v253
	v_mfma_f32_16x16x32_bf16 v[112:115], v[112:115], v[72:75], v[126:129]
	v_xor_b32_e32 v86, 0x80, v252
	ds_read_b64_tr_b16 v[86:87], v86
	ds_read_b64_tr_b16 v[116:117], v116
	v_xor_b32_e32 v118, 0xa0, v252
	ds_read_b64_tr_b16 v[118:119], v118
	v_xor_b32_e32 v126, 0xc0, v253
	ds_read_b64_tr_b16 v[126:127], v126
	v_xor_b32_e32 v120, 0xc0, v252
	ds_read_b64_tr_b16 v[128:129], v120
	v_xor_b32_e32 v120, 0xe0, v253
	v_mfma_f32_16x16x32_bf16 v[100:103], v[100:103], v[72:75], v[122:125]
	v_mfma_f32_16x16x32_bf16 v[122:125], v[130:133], v[72:75], v[134:137]
	ds_read_b64_tr_b16 v[130:131], v120
	v_xor_b32_e32 v111, 0xe0, v252
	ds_read_b64_tr_b16 v[132:133], v111
	s_waitcnt lgkmcnt(0)
; #define GAS __attribute__((address_space(1)))
; __device__ __forceinline__ unsigned pk2(float lo, float hi) { return f2bf(lo) | (f2bf(hi) << 16); }
; template <int L>
; __device__ __forceinline__ void layer_body(const Args& args, LAS unsigned char* lds, const int wave, const int G, const int gw, const int NGW, const int lo, const int hi,
;                                            unsigned char* const ws_kernel, const XcdBarrier& bar, int& pid) {
;     ...
;                             for (int m4 = 0; m4 < 4; ++m4) { const int mt = mh * 4 + m4; const bf16x8 va = (bf16x8){lo[m4][0], lo[m4][1], lo[m4][2], lo[m4][3], hi[m4][0], hi[m4][1], hi[m4][2], hi[m4][3]};
;                                 acc[mt] = __builtin_amdgcn_mfma_f32_16x16x32_bf16(va, pbf[s], acc[mt], 0, 0, 0); }
;                         }
;                     }
;                     const float inv = 1.0f / sum;
;                     GAS bf16* op = (GAS bf16*)(obuf + (size_t)(b * SEQ + r * 64 + c) * D + h * HD + 4 * kg);
; #pragma unroll
;                     for (int mt = 0; mt < 8; ++mt) { v2u w; w.x = pk2(acc[mt][0] * inv, acc[mt][1] * inv); w.y = pk2(acc[mt][2] * inv, acc[mt][3] * inv); *(GAS v2u*)(op + 16 * mt) = w; }
;                     __syncthreads();
	v_div_scale_f32 v111, s[16:17], v104, v104, 1.0
	v_rcp_f32_e32 v120, v111
	v_mfma_f32_16x16x32_bf16 v[84:87], v[84:87], v[72:75], v[88:91]
	s_lshl_b32 s15, s66, 6
	s_add_i32 s15, s15, s8
	s_lshl_b32 s8, s14, 1
	v_fma_f32 v88, -v111, v120, 1.0
	v_fmac_f32_e32 v120, v88, v120
	v_mfma_f32_16x16x32_bf16 v[88:91], v[116:119], v[72:75], v[92:95]
	v_div_scale_f32 v116, vcc, 1.0, v104, 1.0
	v_mul_f32_e32 v117, v116, v120
	v_mfma_f32_16x16x32_bf16 v[92:95], v[126:129], v[72:75], v[96:99]
	s_add_i32 s53, s53, s51
	s_add_i32 s57, s57, s55
	s_nop 0
	v_fma_f32 v96, -v111, v117, v116
	v_fmac_f32_e32 v117, v96, v120
	v_fma_f32 v96, -v111, v117, v116
	v_mfma_f32_16x16x32_bf16 v[72:75], v[130:133], v[72:75], v[76:79]
	v_mov_b32_e32 v97, v82
	v_mov_b32_e32 v82, v81
	s_nop 0
	v_div_fmas_f32 v76, v96, v120, v117
	v_div_fixup_f32 v76, v76, v104, 1.0
	v_mov_b32_e32 v96, v80
	v_or_b32_e32 v78, s15, v110
	v_pk_mul_f32 v[96:97], v[76:77], v[96:97] op_sel_hi:[0,1]
	v_ashrrev_i32_e32 v79, 31, v78
	v_pk_mul_f32 v[80:81], v[76:77], v[82:83] op_sel_hi:[0,1]
	v_lshlrev_b64 v[78:79], 12, v[78:79]
	v_and_b32_sdwa v83, v81, v108 dst_sel:DWORD dst_unused:UNUSED_PAD src0_sel:WORD_1 src1_sel:DWORD
	v_lshl_add_u64 v[78:79], s[6:7], 0, v[78:79]
	v_and_b32_sdwa v77, v97, v108 dst_sel:DWORD dst_unused:UNUSED_PAD src0_sel:WORD_1 src1_sel:DWORD
	v_add3_u32 v81, v81, v83, s64
	v_lshl_add_u64 v[78:79], v[78:79], 0, s[8:9]
	v_lshlrev_b32_e32 v104, 1, v109
	v_add3_u32 v77, v97, v77, s64
	v_and_b32_e32 v81, 0xffff0000, v81
	v_lshl_add_u64 v[78:79], v[78:79], 0, v[104:105]
	v_or_b32_sdwa v81, v81, v77 dst_sel:DWORD dst_unused:UNUSED_PAD src0_sel:DWORD src1_sel:WORD_1
	v_cvt_pk_bf16_f32 v80, v96, v80
	global_store_dwordx2 v[78:79], v[80:81], off
	v_mov_b32_e32 v80, v100
	v_mov_b32_e32 v81, v102
	v_pk_mul_f32 v[80:81], v[76:77], v[80:81] op_sel_hi:[0,1]
	v_mov_b32_e32 v102, v101
	v_pk_mul_f32 v[82:83], v[76:77], v[102:103] op_sel_hi:[0,1]
	v_and_b32_sdwa v77, v81, v108 dst_sel:DWORD dst_unused:UNUSED_PAD src0_sel:WORD_1 src1_sel:DWORD
	v_add3_u32 v77, v81, v77, s64
	v_and_b32_sdwa v81, v83, v108 dst_sel:DWORD dst_unused:UNUSED_PAD src0_sel:WORD_1 src1_sel:DWORD
	v_add3_u32 v81, v83, v81, s64
	v_and_b32_e32 v81, 0xffff0000, v81
	v_or_b32_sdwa v81, v81, v77 dst_sel:DWORD dst_unused:UNUSED_PAD src0_sel:DWORD src1_sel:WORD_1
	v_cvt_pk_bf16_f32 v80, v80, v82
	global_store_dwordx2 v[78:79], v[80:81], off offset:32
	v_mov_b32_e32 v80, v112
	v_mov_b32_e32 v81, v114
	v_pk_mul_f32 v[80:81], v[76:77], v[80:81] op_sel_hi:[0,1]
	v_mov_b32_e32 v114, v113
	v_pk_mul_f32 v[82:83], v[76:77], v[114:115] op_sel_hi:[0,1]
	v_and_b32_sdwa v77, v81, v108 dst_sel:DWORD dst_unused:UNUSED_PAD src0_sel:WORD_1 src1_sel:DWORD
	v_add3_u32 v77, v81, v77, s64
	v_and_b32_sdwa v81, v83, v108 dst_sel:DWORD dst_unused:UNUSED_PAD src0_sel:WORD_1 src1_sel:DWORD
	v_add3_u32 v81, v83, v81, s64
	v_and_b32_e32 v81, 0xffff0000, v81
	v_or_b32_sdwa v81, v81, v77 dst_sel:DWORD dst_unused:UNUSED_PAD src0_sel:DWORD src1_sel:WORD_1
	v_cvt_pk_bf16_f32 v80, v80, v82
	global_store_dwordx2 v[78:79], v[80:81], off offset:64
	v_mov_b32_e32 v80, v122
	v_mov_b32_e32 v81, v124
	v_pk_mul_f32 v[80:81], v[76:77], v[80:81] op_sel_hi:[0,1]
	v_mov_b32_e32 v124, v123
	v_pk_mul_f32 v[82:83], v[76:77], v[124:125] op_sel_hi:[0,1]
	v_and_b32_sdwa v77, v81, v108 dst_sel:DWORD dst_unused:UNUSED_PAD src0_sel:WORD_1 src1_sel:DWORD
	v_add3_u32 v77, v81, v77, s64
	v_and_b32_sdwa v81, v83, v108 dst_sel:DWORD dst_unused:UNUSED_PAD src0_sel:WORD_1 src1_sel:DWORD
	v_add3_u32 v81, v83, v81, s64
	v_and_b32_e32 v81, 0xffff0000, v81
	v_or_b32_sdwa v81, v81, v77 dst_sel:DWORD dst_unused:UNUSED_PAD src0_sel:DWORD src1_sel:WORD_1
	v_cvt_pk_bf16_f32 v80, v80, v82
	global_store_dwordx2 v[78:79], v[80:81], off offset:96
	v_mov_b32_e32 v80, v84
	v_mov_b32_e32 v81, v86
	v_pk_mul_f32 v[80:81], v[76:77], v[80:81] op_sel_hi:[0,1]
	v_mov_b32_e32 v86, v85
	v_pk_mul_f32 v[82:83], v[76:77], v[86:87] op_sel_hi:[0,1]
	v_and_b32_sdwa v77, v81, v108 dst_sel:DWORD dst_unused:UNUSED_PAD src0_sel:WORD_1 src1_sel:DWORD
	v_add3_u32 v77, v81, v77, s64
	v_and_b32_sdwa v81, v83, v108 dst_sel:DWORD dst_unused:UNUSED_PAD src0_sel:WORD_1 src1_sel:DWORD
	v_add3_u32 v81, v83, v81, s64
	v_and_b32_e32 v81, 0xffff0000, v81
	v_or_b32_sdwa v81, v81, v77 dst_sel:DWORD dst_unused:UNUSED_PAD src0_sel:DWORD src1_sel:WORD_1
	v_cvt_pk_bf16_f32 v80, v80, v82
	global_store_dwordx2 v[78:79], v[80:81], off offset:128
	v_mov_b32_e32 v80, v88
	v_mov_b32_e32 v81, v90
	v_pk_mul_f32 v[80:81], v[76:77], v[80:81] op_sel_hi:[0,1]
	v_mov_b32_e32 v90, v89
	v_pk_mul_f32 v[82:83], v[76:77], v[90:91] op_sel_hi:[0,1]
	v_and_b32_sdwa v77, v81, v108 dst_sel:DWORD dst_unused:UNUSED_PAD src0_sel:WORD_1 src1_sel:DWORD
	v_add3_u32 v77, v81, v77, s64
	v_and_b32_sdwa v81, v83, v108 dst_sel:DWORD dst_unused:UNUSED_PAD src0_sel:WORD_1 src1_sel:DWORD
	v_add3_u32 v81, v83, v81, s64
	v_and_b32_e32 v81, 0xffff0000, v81
	v_or_b32_sdwa v81, v81, v77 dst_sel:DWORD dst_unused:UNUSED_PAD src0_sel:DWORD src1_sel:WORD_1
	v_cvt_pk_bf16_f32 v80, v80, v82
	global_store_dwordx2 v[78:79], v[80:81], off offset:160
	v_mov_b32_e32 v80, v92
	v_mov_b32_e32 v81, v94
	v_pk_mul_f32 v[80:81], v[76:77], v[80:81] op_sel_hi:[0,1]
	v_mov_b32_e32 v94, v93
	v_pk_mul_f32 v[82:83], v[76:77], v[94:95] op_sel_hi:[0,1]
	v_and_b32_sdwa v77, v81, v108 dst_sel:DWORD dst_unused:UNUSED_PAD src0_sel:WORD_1 src1_sel:DWORD
	v_add3_u32 v77, v81, v77, s64
	v_and_b32_sdwa v81, v83, v108 dst_sel:DWORD dst_unused:UNUSED_PAD src0_sel:WORD_1 src1_sel:DWORD
	v_add3_u32 v81, v83, v81, s64
	v_and_b32_e32 v81, 0xffff0000, v81
	v_or_b32_sdwa v81, v81, v77 dst_sel:DWORD dst_unused:UNUSED_PAD src0_sel:DWORD src1_sel:WORD_1
	v_cvt_pk_bf16_f32 v80, v80, v82
	global_store_dwordx2 v[78:79], v[80:81], off offset:192
	v_mov_b32_e32 v81, v74
	v_mov_b32_e32 v74, v73
	v_mov_b32_e32 v80, v72
	v_pk_mul_f32 v[72:73], v[76:77], v[74:75] op_sel_hi:[0,1]
	v_pk_mul_f32 v[80:81], v[76:77], v[80:81] op_sel_hi:[0,1]
	v_cvt_pk_bf16_f32 v73, v81, v73
	v_cvt_pk_bf16_f32 v72, v80, v72
	s_andn2_b64 vcc, exec, s[0:1]
	global_store_dwordx2 v[78:79], v[72:73], off offset:224
	s_barrier
	s_cbranch_vccz .LBB0_3541
